# adds: combine-phase loops software-pipelined (next iteration loads prefetched); half unit drops unused B-half DMA
# speedup vs baseline: 1.0090x; 1.0037x over previous
; #define PG8_STAGE(bufoff, gbase, voff) do { _Pragma("unroll") for (int _i = 0; _i < 2; ++_i) \
;         __builtin_amdgcn_global_load_lds((const unsigned*)((const char*)(gbase) + (voff)[_i]), (PG8_LAS unsigned*)(lds + (bufoff) + ldsw + _i * 8192), 16, 0, 0); } while (0)
; #define PG8_LDA(dst, b, h) do { _Pragma("unroll") for (int m = 0; m < 4; ++m) _Pragma("unroll") for (int k = 0; k < 2; ++k) dst[m][k] = *(const PG8_LAS bf16x8*)(lds + PG8_SA(b, h) + aoff + m * 2048 + k * 1024); } while (0)
; template <class Epi, class Sched, bool STAMP = false>
; __device__ __forceinline__ void gemm_phase(PG8_LAS unsigned char* lds, const Gemm g, const Sched& S, const Epi& E, unsigned long long* stamps) {
;     ...
;         for (int t = 0; t < nt; t += 2) {
;             const bool last = (t == nt - 2);
;             const char* a1 = cA + (size_t)(t + 1) * kstep;
;             const char* a2 = last ? nA : cA + (size_t)(t + 2) * kstep; const char* b2 = last ? nB : cB + (size_t)(t + 2) * kstep;
;             const char* a3 = a2 + kstep; const char* b3 = b2 + kstep;
;             if (last && has_next) S.a_ready(nxt);
;             PG8_LDB(B0, 0, 0); PG8_SCHED; PG8_LDA(At, 0, 0); PG8_STAGE(PG8_SA(1, 1), a1 + hstep, voffA);
;             PG8_WAIT_L(8); PG8_BAR; PG8_WAIT_L(0); PG8_MMA(0, 0, At, B0); PG8_BAR; PG8_SCHED;
;             PG8_LDB(B1, 0, 1); PG8_STAGE(PG8_SB(0, 0), b2, voffB);
;             PG8_BAR; PG8_WAIT_L(0); PG8_MMA(0, 1, At, B1); PG8_BAR;
;             PG8_LDA(At, 0, 1); PG8_STAGE(PG8_SA(0, 0), a2, voffA);
;             PG8_BAR; PG8_WAIT_L(0); PG8_MMA(1, 0, At, B0); PG8_BAR; PG8_SCHED;
;             PG8_STAGE(PG8_SB(0, 1), b2 + hstep, voffB);
;             PG8_WAIT_V(6); PG8_BAR; PG8_MMA(1, 1, At, B1); PG8_BAR;
;             PG8_LDB(B0, 1, 0); PG8_SCHED; PG8_LDA(At, 1, 0); PG8_STAGE(PG8_SA(0, 1), a2 + hstep, voffA);
;             PG8_WAIT_L(8); PG8_BAR; PG8_WAIT_L(0); PG8_MMA(0, 0, At, B0); PG8_BAR; PG8_SCHED;
;             PG8_LDB(B1, 1, 1); PG8_STAGE(PG8_SB(1, 0), b3, voffB);
;             PG8_BAR; PG8_WAIT_L(0); PG8_MMA(0, 1, At, B1); PG8_BAR;
;             PG8_LDA(At, 1, 1); PG8_STAGE(PG8_SA(1, 0), a3, voffA);
;             PG8_BAR; PG8_WAIT_L(0); PG8_MMA(1, 0, At, B0); PG8_BAR; PG8_SCHED;
;             PG8_STAGE(PG8_SB(1, 1), b3 + hstep, voffB);
;             PG8_WAIT_V(6); PG8_BAR; PG8_MMA(1, 1, At, B1); PG8_BAR;
;         }
.Lgu1_half_loop:
	ds_read_b128 v[140:143], v148
	ds_read_b128 v[166:169], v149
	ds_read_b128 v[170:173], v150
	ds_read_b128 v[174:177], v151
	s_add_u32 s16, s14, 0x100
	s_addc_u32 s17, s15, 0
	s_cmp_eq_u32 s77, 12
	s_cselect_b32 s29, s5, s17
	s_cselect_b32 s28, s4, s16
	s_cselect_b32 s19, s1, s76
	s_cselect_b32 s18, s0, s75
	s_mov_b32 m0, s68
	ds_read_b128 v[178:181], v146
	ds_read_b128 v[182:185], v146 offset:1024
	ds_read_b128 v[186:189], v146 offset:2048
	ds_read_b128 v[190:193], v146 offset:3072
	ds_read_b128 v[194:197], v146 offset:4096
	ds_read_b128 v[198:201], v146 offset:5120
	ds_read_b128 v[202:205], v146 offset:6144
	ds_read_b128 v[206:209], v146 offset:7168
	global_load_lds_dwordx4 v132, s[14:15]
	s_mov_b32 m0, s69
	s_nop 0
	global_load_lds_dwordx4 v134, s[14:15]
	s_waitcnt lgkmcnt(8)
	s_barrier
	s_waitcnt lgkmcnt(0)
	s_setprio 1
	s_waitcnt lgkmcnt(0)
	v_mfma_f32_16x16x32_bf16 v[124:127], v[140:143], v[178:181], v[124:127]
	v_mfma_f32_16x16x32_bf16 v[120:123], v[170:173], v[178:181], v[120:123]
	v_mfma_f32_16x16x32_bf16 v[108:111], v[140:143], v[186:189], v[108:111]
	v_mfma_f32_16x16x32_bf16 v[104:107], v[170:173], v[186:189], v[104:107]
	v_mfma_f32_16x16x32_bf16 v[92:95], v[140:143], v[194:197], v[92:95]
	v_mfma_f32_16x16x32_bf16 v[88:91], v[170:173], v[194:197], v[88:91]
	v_mfma_f32_16x16x32_bf16 v[76:79], v[140:143], v[202:205], v[76:79]
	v_mfma_f32_16x16x32_bf16 v[72:75], v[170:173], v[202:205], v[72:75]
	v_mfma_f32_16x16x32_bf16 v[124:127], v[166:169], v[182:185], v[124:127]
	v_mfma_f32_16x16x32_bf16 v[120:123], v[174:177], v[182:185], v[120:123]
	v_mfma_f32_16x16x32_bf16 v[108:111], v[166:169], v[190:193], v[108:111]
	v_mfma_f32_16x16x32_bf16 v[104:107], v[174:177], v[190:193], v[104:107]
	v_mfma_f32_16x16x32_bf16 v[92:95], v[166:169], v[198:201], v[92:95]
	v_mfma_f32_16x16x32_bf16 v[88:91], v[174:177], v[198:201], v[88:91]
	v_mfma_f32_16x16x32_bf16 v[76:79], v[166:169], v[206:209], v[76:79]
	v_mfma_f32_16x16x32_bf16 v[72:75], v[174:177], v[206:209], v[72:75]
	s_setprio 0
	s_barrier
	s_mov_b32 m0, s52
	s_nop 0
	global_load_lds_dwordx4 v130, s[18:19]
	s_mov_b32 m0, s53
	s_nop 0
	global_load_lds_dwordx4 v128, s[18:19]
	s_barrier
	s_waitcnt lgkmcnt(0)
	s_setprio 1
	s_waitcnt lgkmcnt(0)
	s_setprio 0
	s_mov_b32 m0, s33
	s_barrier
	ds_read_b128 v[178:181], v146 offset:16384
	ds_read_b128 v[182:185], v146 offset:17408
	ds_read_b128 v[186:189], v146 offset:18432
	ds_read_b128 v[190:193], v146 offset:19456
	ds_read_b128 v[194:197], v146 offset:20480
	ds_read_b128 v[198:201], v146 offset:21504
	ds_read_b128 v[202:205], v146 offset:22528
	ds_read_b128 v[206:209], v146 offset:23552
	global_load_lds_dwordx4 v130, s[28:29]
	s_mov_b32 m0, s54
	s_nop 0
	global_load_lds_dwordx4 v128, s[28:29]
	s_barrier
	s_waitcnt lgkmcnt(0)
	s_setprio 1
	s_waitcnt lgkmcnt(0)
	v_mfma_f32_16x16x32_bf16 v[60:63], v[140:143], v[178:181], v[60:63]
	v_mfma_f32_16x16x32_bf16 v[56:59], v[170:173], v[178:181], v[56:59]
	v_mfma_f32_16x16x32_bf16 v[44:47], v[140:143], v[186:189], v[44:47]
	v_mfma_f32_16x16x32_bf16 v[40:43], v[170:173], v[186:189], v[40:43]
	v_mfma_f32_16x16x32_bf16 v[28:31], v[140:143], v[194:197], v[28:31]
	v_mfma_f32_16x16x32_bf16 v[24:27], v[170:173], v[194:197], v[24:27]
	v_mfma_f32_16x16x32_bf16 v[12:15], v[140:143], v[202:205], v[12:15]
	v_mfma_f32_16x16x32_bf16 v[8:11], v[170:173], v[202:205], v[8:11]
	v_mfma_f32_16x16x32_bf16 v[60:63], v[166:169], v[182:185], v[60:63]
	v_mfma_f32_16x16x32_bf16 v[56:59], v[174:177], v[182:185], v[56:59]
	v_mfma_f32_16x16x32_bf16 v[44:47], v[166:169], v[190:193], v[44:47]
	v_mfma_f32_16x16x32_bf16 v[40:43], v[174:177], v[190:193], v[40:43]
	v_mfma_f32_16x16x32_bf16 v[28:31], v[166:169], v[198:201], v[28:31]
	v_mfma_f32_16x16x32_bf16 v[24:27], v[174:177], v[198:201], v[24:27]
	v_mfma_f32_16x16x32_bf16 v[12:15], v[166:169], v[206:209], v[12:15]
	v_mfma_f32_16x16x32_bf16 v[8:11], v[174:177], v[206:209], v[8:11]
	s_setprio 0
	s_barrier
	s_add_u32 s14, s18, 0x44000
	s_addc_u32 s15, s19, 0
	s_mov_b32 m0, s55
	s_nop 0
	s_mov_b32 m0, s56
	s_nop 0
	s_waitcnt vmcnt(4)
	s_barrier
	s_setprio 1
	s_setprio 0
	s_barrier
	ds_read_b128 v[140:143], v156
	ds_read_b128 v[166:169], v157
	ds_read_b128 v[170:173], v159
	ds_read_b128 v[174:177], v160
	s_add_u32 s14, s28, 0x44000
	s_addc_u32 s15, s29, 0
	s_mov_b32 m0, s57
	ds_read_b128 v[178:181], v146 offset:32768
	ds_read_b128 v[182:185], v146 offset:33792
	ds_read_b128 v[186:189], v146 offset:34816
	ds_read_b128 v[190:193], v146 offset:35840
	ds_read_b128 v[194:197], v146 offset:36864
	ds_read_b128 v[198:201], v146 offset:37888
	ds_read_b128 v[202:205], v146 offset:38912
	ds_read_b128 v[206:209], v146 offset:39936
	global_load_lds_dwordx4 v130, s[14:15]
	s_mov_b32 m0, s58
	s_nop 0
	global_load_lds_dwordx4 v128, s[14:15]
	s_waitcnt lgkmcnt(8)
	s_barrier
	s_waitcnt lgkmcnt(0)
	s_setprio 1
	s_waitcnt lgkmcnt(0)
	v_mfma_f32_16x16x32_bf16 v[124:127], v[140:143], v[178:181], v[124:127]
	v_mfma_f32_16x16x32_bf16 v[120:123], v[170:173], v[178:181], v[120:123]
	v_mfma_f32_16x16x32_bf16 v[108:111], v[140:143], v[186:189], v[108:111]
	v_mfma_f32_16x16x32_bf16 v[104:107], v[170:173], v[186:189], v[104:107]
	v_mfma_f32_16x16x32_bf16 v[92:95], v[140:143], v[194:197], v[92:95]
	v_mfma_f32_16x16x32_bf16 v[88:91], v[170:173], v[194:197], v[88:91]
	v_mfma_f32_16x16x32_bf16 v[76:79], v[140:143], v[202:205], v[76:79]
	v_mfma_f32_16x16x32_bf16 v[72:75], v[170:173], v[202:205], v[72:75]
	v_mfma_f32_16x16x32_bf16 v[124:127], v[166:169], v[182:185], v[124:127]
	v_mfma_f32_16x16x32_bf16 v[120:123], v[174:177], v[182:185], v[120:123]
	v_mfma_f32_16x16x32_bf16 v[108:111], v[166:169], v[190:193], v[108:111]
	v_mfma_f32_16x16x32_bf16 v[104:107], v[174:177], v[190:193], v[104:107]
	v_mfma_f32_16x16x32_bf16 v[92:95], v[166:169], v[198:201], v[92:95]
	v_mfma_f32_16x16x32_bf16 v[88:91], v[174:177], v[198:201], v[88:91]
	v_mfma_f32_16x16x32_bf16 v[76:79], v[166:169], v[206:209], v[76:79]
	v_mfma_f32_16x16x32_bf16 v[72:75], v[174:177], v[206:209], v[72:75]
	s_setprio 0
	s_barrier
; #define PG8_STAGE(bufoff, gbase, voff) do { _Pragma("unroll") for (int _i = 0; _i < 2; ++_i) \
;         __builtin_amdgcn_global_load_lds((const unsigned*)((const char*)(gbase) + (voff)[_i]), (PG8_LAS unsigned*)(lds + (bufoff) + ldsw + _i * 8192), 16, 0, 0); } while (0)
; #define PG8_LDA(dst, b, h) do { _Pragma("unroll") for (int m = 0; m < 4; ++m) _Pragma("unroll") for (int k = 0; k < 2; ++k) dst[m][k] = *(const PG8_LAS bf16x8*)(lds + PG8_SA(b, h) + aoff + m * 2048 + k * 1024); } while (0)
; template <class Epi, class Sched, bool STAMP = false>
; __device__ __forceinline__ void gemm_phase(PG8_LAS unsigned char* lds, const Gemm g, const Sched& S, const Epi& E, unsigned long long* stamps) {
;     ...
;         for (int t = 0; t < nt; t += 2) {
;             const bool last = (t == nt - 2);
;             const char* a1 = cA + (size_t)(t + 1) * kstep;
;             const char* a2 = last ? nA : cA + (size_t)(t + 2) * kstep; const char* b2 = last ? nB : cB + (size_t)(t + 2) * kstep;
;             const char* a3 = a2 + kstep; const char* b3 = b2 + kstep;
;             if (last && has_next) S.a_ready(nxt);
;             PG8_LDB(B0, 0, 0); PG8_SCHED; PG8_LDA(At, 0, 0); PG8_STAGE(PG8_SA(1, 1), a1 + hstep, voffA);
;             PG8_WAIT_L(8); PG8_BAR; PG8_WAIT_L(0); PG8_MMA(0, 0, At, B0); PG8_BAR; PG8_SCHED;
;             PG8_LDB(B1, 0, 1); PG8_STAGE(PG8_SB(0, 0), b2, voffB);
;             PG8_BAR; PG8_WAIT_L(0); PG8_MMA(0, 1, At, B1); PG8_BAR;
;             PG8_LDA(At, 0, 1); PG8_STAGE(PG8_SA(0, 0), a2, voffA);
;             PG8_BAR; PG8_WAIT_L(0); PG8_MMA(1, 0, At, B0); PG8_BAR; PG8_SCHED;
;             PG8_STAGE(PG8_SB(0, 1), b2 + hstep, voffB);
;             PG8_WAIT_V(6); PG8_BAR; PG8_MMA(1, 1, At, B1); PG8_BAR;
;             PG8_LDB(B0, 1, 0); PG8_SCHED; PG8_LDA(At, 1, 0); PG8_STAGE(PG8_SA(0, 1), a2 + hstep, voffA);
;             PG8_WAIT_L(8); PG8_BAR; PG8_WAIT_L(0); PG8_MMA(0, 0, At, B0); PG8_BAR; PG8_SCHED;
;             PG8_LDB(B1, 1, 1); PG8_STAGE(PG8_SB(1, 0), b3, voffB);
;             PG8_BAR; PG8_WAIT_L(0); PG8_MMA(0, 1, At, B1); PG8_BAR;
;             PG8_LDA(At, 1, 1); PG8_STAGE(PG8_SA(1, 0), a3, voffA);
;             PG8_BAR; PG8_WAIT_L(0); PG8_MMA(1, 0, At, B0); PG8_BAR; PG8_SCHED;
;             PG8_STAGE(PG8_SB(1, 1), b3 + hstep, voffB);
;             PG8_WAIT_V(6); PG8_BAR; PG8_MMA(1, 1, At, B1); PG8_BAR;
;         }
	s_mov_b32 m0, s61
	s_add_u32 s100, s18, 0x80
	s_addc_u32 s101, s19, 0
	global_load_lds_dwordx4 v130, s[100:101]
	s_mov_b32 m0, s62
	s_nop 0
	global_load_lds_dwordx4 v128, s[100:101]
	s_barrier
	s_waitcnt lgkmcnt(0)
	s_setprio 1
	s_waitcnt lgkmcnt(0)
	s_setprio 0
	s_mov_b32 m0, s63
	s_barrier
	ds_read_b128 v[178:181], v146 offset:49152
	ds_read_b128 v[182:185], v146 offset:50176
	ds_read_b128 v[186:189], v146 offset:51200
	ds_read_b128 v[190:193], v146 offset:52224
	ds_read_b128 v[194:197], v146 offset:53248
	ds_read_b128 v[198:201], v146 offset:54272
	ds_read_b128 v[202:205], v146 offset:55296
	ds_read_b128 v[206:209], v146 offset:56320
	s_add_u32 s100, s28, 0x80
	s_addc_u32 s101, s29, 0
	global_load_lds_dwordx4 v130, s[100:101]
	s_mov_b32 m0, s64
	s_nop 0
	global_load_lds_dwordx4 v128, s[100:101]
	s_barrier
	s_waitcnt lgkmcnt(0)
	s_setprio 1
	s_waitcnt lgkmcnt(0)
	v_mfma_f32_16x16x32_bf16 v[60:63], v[140:143], v[178:181], v[60:63]
	v_mfma_f32_16x16x32_bf16 v[56:59], v[170:173], v[178:181], v[56:59]
	v_mfma_f32_16x16x32_bf16 v[44:47], v[140:143], v[186:189], v[44:47]
	v_mfma_f32_16x16x32_bf16 v[40:43], v[170:173], v[186:189], v[40:43]
	v_mfma_f32_16x16x32_bf16 v[28:31], v[140:143], v[194:197], v[28:31]
	v_mfma_f32_16x16x32_bf16 v[24:27], v[170:173], v[194:197], v[24:27]
	v_mfma_f32_16x16x32_bf16 v[12:15], v[140:143], v[202:205], v[12:15]
	v_mfma_f32_16x16x32_bf16 v[8:11], v[170:173], v[202:205], v[8:11]
	v_mfma_f32_16x16x32_bf16 v[60:63], v[166:169], v[182:185], v[60:63]
	v_mfma_f32_16x16x32_bf16 v[56:59], v[174:177], v[182:185], v[56:59]
	v_mfma_f32_16x16x32_bf16 v[44:47], v[166:169], v[190:193], v[44:47]
	v_mfma_f32_16x16x32_bf16 v[40:43], v[174:177], v[190:193], v[40:43]
	v_mfma_f32_16x16x32_bf16 v[28:31], v[166:169], v[198:201], v[28:31]
	v_mfma_f32_16x16x32_bf16 v[24:27], v[174:177], v[198:201], v[24:27]
	v_mfma_f32_16x16x32_bf16 v[12:15], v[166:169], v[206:209], v[12:15]
	v_mfma_f32_16x16x32_bf16 v[8:11], v[174:177], v[206:209], v[8:11]
	s_setprio 0
	s_barrier
	s_add_u32 s14, s18, 0x44080
	s_addc_u32 s15, s19, 0
	s_mov_b32 m0, s65
	s_nop 0
	s_mov_b32 m0, s66
	s_nop 0
	s_waitcnt vmcnt(4)
	s_barrier
	s_setprio 1
	s_setprio 0
	s_add_i32 s77, s77, 2
	s_add_u32 s75, s75, 0x100
	s_addc_u32 s76, s76, 0
	s_cmp_gt_u32 s77, 13
	s_mov_b64 s[14:15], s[16:17]
	s_barrier
	s_cbranch_scc0 .Lgu1_half_loop
; DI float ex2(float x) { return __builtin_amdgcn_exp2f(x); }
;     DI void operator()(const f32x4 (&acc)[2][2][4][2], const Unit& u, int wr, int wc, int fr, int fq) const {
;         const int row0 = u.pm * BM + wr * 64 + fr, hcol0 = ((u.pn * BM + wc * 32) >> 1) + 4 * fq;
; #pragma unroll
;         for (int ai = 0; ai < 2; ++ai)
; #pragma unroll
;             for (int m = 0; m < 4; ++m) { u16* rowp = O + (size_t)(row0 + ai * HALF + m * 16) * ldc + hcol0;
; #pragma unroll
;                 for (int bj = 0; bj < 2; ++bj) { const f32x4 g = acc[ai][bj][m][0], up = acc[ai][bj][m][1]; float r[4];
; #pragma unroll
;                     for (int j = 0; j < 4; ++j) r[j] = g[j] * up[j] * __builtin_amdgcn_rcpf(1.f + ex2(-LOG2E * g[j]));
;                     uint2 w = {pack2(r[0], r[1]), pack2(r[2], r[3])}; *(uint2*)(rowp + bj * (HALF / 2)) = w; } }
	v_exp_f32_e64 v168, -v124
	v_exp_f32_e64 v169, -v125
	v_exp_f32_e64 v170, -v126
	v_exp_f32_e64 v171, -v127
	v_add_f32_e32 v168, 1.0, v168
	v_add_f32_e32 v169, 1.0, v169
	v_add_f32_e32 v170, 1.0, v170
	v_add_f32_e32 v171, 1.0, v171
	v_rcp_f32_e32 v168, v168
	v_rcp_f32_e32 v169, v169
	v_rcp_f32_e32 v170, v170
	v_rcp_f32_e32 v171, v171
	s_lshl_b32 s10, s74, 8
	v_pk_mul_f32 v[122:123], v[126:127], v[122:123]
	v_pk_mul_f32 v[120:121], v[124:125], v[120:121]
	s_or_b32 s10, s10, s60
	s_or_b32 s10, s10, s98
	v_pk_mul_f32 v[120:121], v[120:121], v[168:169]
	v_pk_mul_f32 v[122:123], v[122:123], v[170:171]
	s_ashr_i32 s10, s10, 1
	v_cvt_pk_bf16_f32 v120, v120, v121
	v_cvt_pk_bf16_f32 v121, v122, v123
	v_or_b32_e32 v140, s10, v147
	v_lshl_add_u32 v165, s73, 8, v145
	v_ashrrev_i32_e32 v141, 31, v140
	v_mov_b64_e32 v[142:143], s[12:13]
	v_mad_i64_i32 v[166:167], s[14:15], v165, s70, v[142:143]
	v_lshlrev_b64 v[140:141], 1, v[140:141]
	v_lshl_add_u64 v[166:167], v[166:167], 0, v[140:141]
	global_store_dwordx2 v[166:167], v[120:121], off
	v_exp_f32_e64 v114, -v108
	v_exp_f32_e64 v115, -v109
	v_exp_f32_e64 v116, -v110
	v_exp_f32_e64 v117, -v111
	v_add_f32_e32 v114, 1.0, v114
	v_add_f32_e32 v115, 1.0, v115
	v_add_f32_e32 v116, 1.0, v116
	v_add_f32_e32 v117, 1.0, v117
	v_rcp_f32_e32 v114, v114
	v_rcp_f32_e32 v115, v115
	v_rcp_f32_e32 v116, v116
	v_rcp_f32_e32 v117, v117
	v_pk_mul_f32 v[106:107], v[110:111], v[106:107]
	v_pk_mul_f32 v[104:105], v[108:109], v[104:105]
	v_pk_mul_f32 v[104:105], v[104:105], v[114:115]
	v_pk_mul_f32 v[106:107], v[106:107], v[116:117]
	v_cvt_pk_bf16_f32 v104, v104, v105
	v_cvt_pk_bf16_f32 v105, v106, v107
	v_or_b32_e32 v112, 16, v165
	v_mad_i64_i32 v[112:113], s[14:15], v112, s70, v[142:143]
	v_lshl_add_u64 v[112:113], v[112:113], 0, v[140:141]
	global_store_dwordx2 v[112:113], v[104:105], off
	v_exp_f32_e64 v98, -v92
	v_exp_f32_e64 v99, -v93
	v_exp_f32_e64 v100, -v94
	v_exp_f32_e64 v101, -v95
	v_add_f32_e32 v98, 1.0, v98
	v_add_f32_e32 v99, 1.0, v99
	v_add_f32_e32 v100, 1.0, v100
	v_add_f32_e32 v101, 1.0, v101
	v_rcp_f32_e32 v98, v98
	v_rcp_f32_e32 v99, v99
	v_rcp_f32_e32 v100, v100
	v_rcp_f32_e32 v101, v101
	v_pk_mul_f32 v[90:91], v[94:95], v[90:91]
	v_pk_mul_f32 v[88:89], v[92:93], v[88:89]
	v_pk_mul_f32 v[88:89], v[88:89], v[98:99]
	v_pk_mul_f32 v[90:91], v[90:91], v[100:101]
	v_cvt_pk_bf16_f32 v88, v88, v89
	v_cvt_pk_bf16_f32 v89, v90, v91
	v_or_b32_e32 v96, 32, v165
	v_mad_i64_i32 v[96:97], s[14:15], v96, s70, v[142:143]
	v_lshl_add_u64 v[96:97], v[96:97], 0, v[140:141]
	global_store_dwordx2 v[96:97], v[88:89], off
	v_exp_f32_e64 v82, -v76
	v_exp_f32_e64 v83, -v77
	v_exp_f32_e64 v84, -v78
	v_exp_f32_e64 v85, -v79
	v_add_f32_e32 v82, 1.0, v82
	v_add_f32_e32 v83, 1.0, v83
	v_add_f32_e32 v84, 1.0, v84
	v_add_f32_e32 v85, 1.0, v85
	v_rcp_f32_e32 v82, v82
	v_rcp_f32_e32 v83, v83
	v_rcp_f32_e32 v84, v84
	v_rcp_f32_e32 v85, v85
	v_pk_mul_f32 v[74:75], v[78:79], v[74:75]
	v_pk_mul_f32 v[72:73], v[76:77], v[72:73]
	v_pk_mul_f32 v[72:73], v[72:73], v[82:83]
	v_pk_mul_f32 v[74:75], v[74:75], v[84:85]
	v_cvt_pk_bf16_f32 v72, v72, v73
	v_cvt_pk_bf16_f32 v73, v74, v75
	v_or_b32_e32 v80, 48, v165
	v_mad_i64_i32 v[80:81], s[14:15], v80, s70, v[142:143]
	v_lshl_add_u64 v[80:81], v[80:81], 0, v[140:141]
	global_store_dwordx2 v[80:81], v[72:73], off
	v_exp_f32_e64 v66, -v60
	v_exp_f32_e64 v67, -v61
	v_exp_f32_e64 v68, -v62
	v_exp_f32_e64 v69, -v63
	v_add_f32_e32 v66, 1.0, v66
	v_add_f32_e32 v67, 1.0, v67
	v_add_f32_e32 v68, 1.0, v68
	v_add_f32_e32 v69, 1.0, v69
	v_rcp_f32_e32 v66, v66
	v_rcp_f32_e32 v67, v67
	v_rcp_f32_e32 v68, v68
	v_rcp_f32_e32 v69, v69
	v_pk_mul_f32 v[58:59], v[62:63], v[58:59]
	v_pk_mul_f32 v[56:57], v[60:61], v[56:57]
	v_pk_mul_f32 v[56:57], v[56:57], v[66:67]
	v_pk_mul_f32 v[58:59], v[58:59], v[68:69]
	v_cvt_pk_bf16_f32 v56, v56, v57
	v_cvt_pk_bf16_f32 v57, v58, v59
	v_add_u32_e32 v64, 0x80, v165
	v_mad_i64_i32 v[64:65], s[14:15], v64, s70, v[142:143]
	v_lshl_add_u64 v[64:65], v[64:65], 0, v[140:141]
	global_store_dwordx2 v[64:65], v[56:57], off
	v_exp_f32_e64 v50, -v44
	v_exp_f32_e64 v51, -v45
	v_exp_f32_e64 v52, -v46
	v_exp_f32_e64 v53, -v47
	v_add_f32_e32 v50, 1.0, v50
	v_add_f32_e32 v51, 1.0, v51
	v_add_f32_e32 v52, 1.0, v52
	v_add_f32_e32 v53, 1.0, v53
	v_rcp_f32_e32 v50, v50
	v_rcp_f32_e32 v51, v51
	v_rcp_f32_e32 v52, v52
	v_rcp_f32_e32 v53, v53
	v_pk_mul_f32 v[42:43], v[46:47], v[42:43]
	v_pk_mul_f32 v[40:41], v[44:45], v[40:41]
	v_pk_mul_f32 v[40:41], v[40:41], v[50:51]
	v_pk_mul_f32 v[42:43], v[42:43], v[52:53]
	v_cvt_pk_bf16_f32 v40, v40, v41
	v_cvt_pk_bf16_f32 v41, v42, v43
	v_add_u32_e32 v48, 0x90, v165
	v_mad_i64_i32 v[48:49], s[14:15], v48, s70, v[142:143]
	v_lshl_add_u64 v[48:49], v[48:49], 0, v[140:141]
	global_store_dwordx2 v[48:49], v[40:41], off
	v_exp_f32_e64 v34, -v28
	v_exp_f32_e64 v35, -v29
	v_exp_f32_e64 v36, -v30
	v_exp_f32_e64 v37, -v31
	v_add_f32_e32 v34, 1.0, v34
	v_add_f32_e32 v35, 1.0, v35
	v_add_f32_e32 v36, 1.0, v36
	v_add_f32_e32 v37, 1.0, v37
	v_rcp_f32_e32 v34, v34
	v_rcp_f32_e32 v35, v35
	v_rcp_f32_e32 v36, v36
	v_rcp_f32_e32 v37, v37
	v_pk_mul_f32 v[26:27], v[30:31], v[26:27]
	v_pk_mul_f32 v[24:25], v[28:29], v[24:25]
	v_pk_mul_f32 v[24:25], v[24:25], v[34:35]
	v_pk_mul_f32 v[26:27], v[26:27], v[36:37]
	v_cvt_pk_bf16_f32 v24, v24, v25
	v_cvt_pk_bf16_f32 v25, v26, v27
	v_add_u32_e32 v32, 0xa0, v165
	v_mad_i64_i32 v[32:33], s[14:15], v32, s70, v[142:143]
	v_lshl_add_u64 v[32:33], v[32:33], 0, v[140:141]
	global_store_dwordx2 v[32:33], v[24:25], off
	v_exp_f32_e64 v18, -v12
	v_exp_f32_e64 v19, -v13
	v_exp_f32_e64 v20, -v14
	v_exp_f32_e64 v21, -v15
	v_add_f32_e32 v18, 1.0, v18
	v_add_f32_e32 v19, 1.0, v19
	v_add_f32_e32 v20, 1.0, v20
	v_add_f32_e32 v21, 1.0, v21
	v_rcp_f32_e32 v18, v18
	v_rcp_f32_e32 v19, v19
	v_rcp_f32_e32 v20, v20
	v_rcp_f32_e32 v21, v21
	v_pk_mul_f32 v[10:11], v[14:15], v[10:11]
	v_pk_mul_f32 v[8:9], v[12:13], v[8:9]
	v_pk_mul_f32 v[8:9], v[8:9], v[18:19]
	v_pk_mul_f32 v[10:11], v[10:11], v[20:21]
	v_cvt_pk_bf16_f32 v8, v8, v9
	v_cvt_pk_bf16_f32 v9, v10, v11
	v_add_u32_e32 v16, 0xb0, v165
	v_mad_i64_i32 v[16:17], s[14:15], v16, s70, v[142:143]
	v_lshl_add_u64 v[16:17], v[16:17], 0, v[140:141]
	global_store_dwordx2 v[16:17], v[8:9], off
	s_and_b64 vcc, exec, s[2:3]
	s_mov_b32 s74, s71
	s_mov_b32 s73, s72
	s_mov_b64 s[16:17], s[0:1]
	s_mov_b64 s[14:15], s[4:5]

; DI float bflo(unsigned u) { return __uint_as_float(u << 16); }
; DI float bfhi(unsigned u) { return __uint_as_float(u & 0xffff0000u); }
; DI int ltid() { int t = threadIdx.x; asm volatile("" : "+v"(t)); return t; }
; DI int lbid() { int b = blockIdx.x; asm volatile("" : "+s"(b)); return b; }
; DI void combine_phase(const Params& p, int layer) {
;     ...
;   for (int idx = lbid() * NTHR + ltid(); idx < total; idx += gridDim.x * NTHR) {
;     const int tok = idx / 48, ch = idx - tok * 48, head = ch >> 3;
;     float acc[8] = {0, 0, 0, 0, 0, 0, 0, 0};
;     float lsum = 0.f;
; #pragma unroll
;     for (int b = 0; b < 3; ++b) {
;       const uint4 v = *(const uint4*)(part + (size_t)b * S * 384 + (size_t)tok * 384 + ch * 8);
;       lsum += lpart[(size_t)b * S * 8 + (size_t)tok * 8 + head];
;       acc[0] += bflo(v.x); acc[1] += bfhi(v.x);
;       acc[2] += bflo(v.y); acc[3] += bfhi(v.y);
;       acc[4] += bflo(v.z); acc[5] += bfhi(v.z);
;       acc[6] += bflo(v.w); acc[7] += bfhi(v.w);
;     }
;     const float inv = 1.f / lsum;
;     uint4 o = {pack2(acc[0] * inv, acc[1] * inv), pack2(acc[2] * inv, acc[3] * inv), pack2(acc[4] * inv, acc[5] * inv),
;                pack2(acc[6] * inv, acc[7] * inv)};
;     *(uint4*)(mixed + (size_t)tok * LDH + ch * 8) = o;
;   }
.LBB0_275:
	s_or_b64 exec, exec, s[0:1]
	s_mov_b32 s2, s92
	v_mov_b32_e32 v1, v158
	s_barrier
	s_mov_b32 s0, 0xc0000
	v_lshl_add_u32 v0, s2, 9, v1
	v_cmp_gt_i32_e32 vcc, s0, v0
	s_and_saveexec_b64 s[0:1], vcc
	s_cbranch_execz .LBB0_278
	v_lshlrev_b32_e32 v1, 3, v1
	s_lshl_b32 s4, s11, 9
	v_lshl_add_u32 v2, s2, 12, v1
	s_lshl_b32 s5, s11, 12
	s_mov_b64 s[2:3], 0
	s_mov_b32 s6, 0x2aaaaaab
	s_movk_i32 s7, 0xffd0
	s_movk_i32 s10, 0x300
	v_mov_b64_e32 v[4:5], s[14:15]
	s_movk_i32 s30, 0xfe80
	s_mov_b32 s31, 0xc00000
	s_mov_b32 s33, 0x80000
	s_mov_b32 s34, 0x1800000
	s_mov_b32 s35, 0x100000
	s_movk_i32 s36, 0x880
	v_mov_b64_e32 v[6:7], s[26:27]
	s_mov_b32 s37, 0xbffff
	v_mov_b32_e32 v100, v0
	v_mov_b32_e32 v102, v2
	v_mul_hi_i32 v101, v100, s6
	v_lshrrev_b32_e32 v103, 31, v101
	v_ashrrev_i32_e32 v101, 3, v101
	v_add_u32_e32 v120, v101, v103
	v_mad_u64_u32 v[108:109], s[52:53], v120, s7, v[100:101]
	v_mad_u64_u32 v[112:113], s[52:53], v120, s30, v[102:103]
	v_ashrrev_i32_e32 v108, 3, v108
	v_ashrrev_i32_e32 v113, 31, v112
	v_ashrrev_i32_e32 v121, 31, v120
	v_mad_i64_i32 v[110:111], s[52:53], v120, s10, v[4:5]
	v_lshlrev_b64 v[122:123], 1, v[112:113]
	v_ashrrev_i32_e32 v109, 31, v108
	v_lshlrev_b64 v[114:115], 5, v[120:121]
	v_lshl_add_u64 v[112:113], v[110:111], 0, v[122:123]
	v_lshl_add_u64 v[116:117], v[108:109], 2, s[28:29]
	v_lshl_add_u64 v[124:125], v[116:117], 0, v[114:115]
	v_add_co_u32_e32 v114, vcc, s31, v112
	global_load_dwordx4 v[108:111], v[112:113], off
	s_nop 1
	v_addc_co_u32_e32 v115, vcc, 0, v113, vcc
	v_add_co_u32_e32 v116, vcc, s34, v112
	s_nop 1
	v_addc_co_u32_e32 v117, vcc, 0, v113, vcc
	v_add_co_u32_e32 v126, vcc, s33, v124
	global_load_dword v101, v[124:125], off
	global_load_dwordx4 v[112:115], v[114:115], off
	global_load_dwordx4 v[116:119], v[116:117], off
	s_nop 1
	v_addc_co_u32_e32 v127, vcc, 0, v125, vcc
	v_add_co_u32_e32 v124, vcc, s35, v124
	s_nop 1
	v_addc_co_u32_e32 v125, vcc, 0, v125, vcc
	global_load_dword v103, v[126:127], off
	global_load_dword v134, v[124:125], off
	s_waitcnt vmcnt(0)
	s_branch .Lpl1_aw
.Lpl1_top:
	s_waitcnt vmcnt(1)
.Lpl1_aw:
	v_mul_hi_i32 v1, v0, s6
	v_lshrrev_b32_e32 v3, 31, v1
	v_ashrrev_i32_e32 v1, 3, v1
	v_add_u32_e32 v20, v1, v3
	v_mad_u64_u32 v[8:9], s[52:53], v20, s7, v[0:1]
	v_mad_u64_u32 v[12:13], s[52:53], v20, s30, v[2:3]
	v_ashrrev_i32_e32 v8, 3, v8
	v_ashrrev_i32_e32 v13, 31, v12
	v_ashrrev_i32_e32 v21, 31, v20
	v_mad_i64_i32 v[10:11], s[52:53], v20, s10, v[4:5]
	v_lshlrev_b64 v[22:23], 1, v[12:13]
	v_ashrrev_i32_e32 v9, 31, v8
	v_lshlrev_b64 v[14:15], 5, v[20:21]
	v_lshl_add_u64 v[12:13], v[10:11], 0, v[22:23]
	v_lshl_add_u64 v[16:17], v[8:9], 2, s[28:29]
	v_lshl_add_u64 v[24:25], v[16:17], 0, v[14:15]
	v_add_co_u32_e32 v14, vcc, s31, v12
	v_mov_b64_e32 v[8:9], v[108:109]
	v_mov_b64_e32 v[10:11], v[110:111]
	s_nop 0
	v_addc_co_u32_e32 v15, vcc, 0, v13, vcc
	v_add_co_u32_e32 v16, vcc, s34, v12
	v_mad_i64_i32 v[20:21], s[52:53], v20, s36, v[6:7]
	s_nop 0
	v_addc_co_u32_e32 v17, vcc, 0, v13, vcc
	v_add_co_u32_e32 v26, vcc, s33, v24
	v_mov_b32_e32 v1, v101
	s_nop 0
	v_mov_b64_e32 v[12:13], v[112:113]
	v_mov_b64_e32 v[14:15], v[114:115]
	s_nop 0
	v_mov_b64_e32 v[16:17], v[116:117]
	v_mov_b64_e32 v[18:19], v[118:119]
	v_addc_co_u32_e32 v27, vcc, 0, v25, vcc
	v_add_co_u32_e32 v24, vcc, s35, v24
	v_lshl_add_u64 v[20:21], v[20:21], 0, v[22:23]
	s_nop 0
	v_addc_co_u32_e32 v25, vcc, 0, v25, vcc
	v_mov_b32_e32 v3, v103
	v_mov_b32_e32 v34, v134
	v_add_u32_e32 v0, s4, v0
	v_cmp_lt_i32_e32 vcc, s37, v0
	s_or_b64 s[2:3], vcc, s[2:3]
	v_add_u32_e32 v2, s5, v2
	s_mov_b64 s[98:99], exec
	s_andn2_b64 exec, exec, s[2:3]
	s_cbranch_execz .Lpl1_np
	v_mov_b32_e32 v100, v0
	v_mov_b32_e32 v102, v2
	v_mul_hi_i32 v101, v100, s6
	v_lshrrev_b32_e32 v103, 31, v101
	v_ashrrev_i32_e32 v101, 3, v101
	v_add_u32_e32 v120, v101, v103
	v_mad_u64_u32 v[108:109], s[52:53], v120, s7, v[100:101]
	v_mad_u64_u32 v[112:113], s[52:53], v120, s30, v[102:103]
	v_ashrrev_i32_e32 v108, 3, v108
	v_ashrrev_i32_e32 v113, 31, v112
	v_ashrrev_i32_e32 v121, 31, v120
	v_mad_i64_i32 v[110:111], s[52:53], v120, s10, v[4:5]
	v_lshlrev_b64 v[122:123], 1, v[112:113]
	v_ashrrev_i32_e32 v109, 31, v108
	v_lshlrev_b64 v[114:115], 5, v[120:121]
	v_lshl_add_u64 v[112:113], v[110:111], 0, v[122:123]
	v_lshl_add_u64 v[116:117], v[108:109], 2, s[28:29]
	v_lshl_add_u64 v[124:125], v[116:117], 0, v[114:115]
	v_add_co_u32_e32 v114, vcc, s31, v112
	global_load_dwordx4 v[108:111], v[112:113], off
	s_nop 1
	v_addc_co_u32_e32 v115, vcc, 0, v113, vcc
	v_add_co_u32_e32 v116, vcc, s34, v112
	s_nop 1
	v_addc_co_u32_e32 v117, vcc, 0, v113, vcc
	v_add_co_u32_e32 v126, vcc, s33, v124
	global_load_dword v101, v[124:125], off
	global_load_dwordx4 v[112:115], v[114:115], off
	global_load_dwordx4 v[116:119], v[116:117], off
	s_nop 1
	v_addc_co_u32_e32 v127, vcc, 0, v125, vcc
	v_add_co_u32_e32 v124, vcc, s35, v124
	s_nop 1
	v_addc_co_u32_e32 v125, vcc, 0, v125, vcc
	global_load_dword v103, v[126:127], off
	global_load_dword v134, v[124:125], off
; DI float bflo(unsigned u) { return __uint_as_float(u << 16); }
; DI float bfhi(unsigned u) { return __uint_as_float(u & 0xffff0000u); }
; DI void combine_phase(const Params& p, int layer) {
;     ...
;     for (int b = 0; b < 3; ++b) {
;       const uint4 v = *(const uint4*)(part + (size_t)b * S * 384 + (size_t)tok * 384 + ch * 8);
;       lsum += lpart[(size_t)b * S * 8 + (size_t)tok * 8 + head];
;       acc[0] += bflo(v.x); acc[1] += bfhi(v.x);
;       acc[2] += bflo(v.y); acc[3] += bfhi(v.y);
;       acc[4] += bflo(v.z); acc[5] += bfhi(v.z);
;       acc[6] += bflo(v.w); acc[7] += bfhi(v.w);
;     }
;     const float inv = 1.f / lsum;
;     uint4 o = {pack2(acc[0] * inv, acc[1] * inv), pack2(acc[2] * inv, acc[3] * inv), pack2(acc[4] * inv, acc[5] * inv),
;                pack2(acc[6] * inv, acc[7] * inv)};
;     *(uint4*)(mixed + (size_t)tok * LDH + ch * 8) = o;
;   }
.Lpl1_np:
	s_mov_b64 exec, s[98:99]
	v_lshlrev_b32_e32 v22, 16, v8
	v_and_b32_e32 v23, 0xffff0000, v8
	v_lshlrev_b32_e32 v8, 16, v9
	v_and_b32_e32 v9, 0xffff0000, v9
	v_pk_add_f32 v[8:9], v[8:9], 0 op_sel_hi:[1,0]
	v_lshlrev_b32_e32 v24, 16, v10
	v_and_b32_e32 v25, 0xffff0000, v10
	v_lshlrev_b32_e32 v10, 16, v11
	v_and_b32_e32 v11, 0xffff0000, v11
	v_add_f32_e32 v1, 0, v1
	v_lshlrev_b32_e32 v26, 16, v12
	v_and_b32_e32 v27, 0xffff0000, v12
	v_lshlrev_b32_e32 v12, 16, v13
	v_and_b32_e32 v13, 0xffff0000, v13
	v_lshlrev_b32_e32 v30, 16, v16
	v_and_b32_e32 v31, 0xffff0000, v16
	v_lshlrev_b32_e32 v16, 16, v17
	v_and_b32_e32 v17, 0xffff0000, v17
	v_add_f32_e32 v1, v1, v3
	v_add_f32_e32 v1, v1, v34
	v_pk_add_f32 v[8:9], v[8:9], v[12:13]
	v_div_scale_f32 v3, s[52:53], v1, v1, 1.0
	v_pk_add_f32 v[8:9], v[8:9], v[16:17]
	v_rcp_f32_e32 v17, v3
	v_lshlrev_b32_e32 v28, 16, v14
	v_and_b32_e32 v29, 0xffff0000, v14
	v_lshlrev_b32_e32 v14, 16, v15
	v_and_b32_e32 v15, 0xffff0000, v15
	v_pk_add_f32 v[10:11], v[10:11], 0 op_sel_hi:[1,0]
	v_lshlrev_b32_e32 v32, 16, v18
	v_and_b32_e32 v33, 0xffff0000, v18
	v_lshlrev_b32_e32 v18, 16, v19
	v_and_b32_e32 v19, 0xffff0000, v19
	v_pk_add_f32 v[10:11], v[10:11], v[14:15]
	v_div_scale_f32 v16, vcc, 1.0, v1, 1.0
	v_pk_add_f32 v[10:11], v[10:11], v[18:19]
	v_fma_f32 v18, -v3, v17, 1.0
	v_fmac_f32_e32 v17, v18, v17
	v_mul_f32_e32 v18, v16, v17
	v_fma_f32 v19, -v3, v18, v16
	v_fmac_f32_e32 v18, v19, v17
	v_pk_add_f32 v[22:23], v[22:23], 0 op_sel_hi:[1,0]
	v_pk_add_f32 v[24:25], v[24:25], 0 op_sel_hi:[1,0]
	v_fma_f32 v3, -v3, v18, v16
	v_pk_add_f32 v[22:23], v[22:23], v[26:27]
	v_pk_add_f32 v[12:13], v[24:25], v[28:29]
	v_div_fmas_f32 v3, v3, v17, v18
	v_pk_add_f32 v[14:15], v[22:23], v[30:31]
	v_pk_add_f32 v[12:13], v[12:13], v[32:33]
	v_div_fixup_f32 v16, v3, v1, 1.0
	v_pk_mul_f32 v[14:15], v[14:15], v[16:17] op_sel_hi:[1,0]
	v_pk_mul_f32 v[18:19], v[8:9], v[16:17] op_sel_hi:[1,0]
	v_pk_mul_f32 v[12:13], v[12:13], v[16:17] op_sel_hi:[1,0]
	v_pk_mul_f32 v[16:17], v[16:17], v[10:11] op_sel_hi:[0,1]
	v_cvt_pk_bf16_f32 v8, v14, v15
	v_cvt_pk_bf16_f32 v9, v18, v19
	v_cvt_pk_bf16_f32 v10, v12, v13
	v_cvt_pk_bf16_f32 v11, v16, v17
	global_store_dwordx4 v[20:21], v[8:11], off
	s_andn2_b64 exec, exec, s[2:3]
	s_cbranch_execnz .Lpl1_top

; DI int ltid() { int t = threadIdx.x; asm volatile("" : "+v"(t)); return t; }
; DI int lbid() { int b = blockIdx.x; asm volatile("" : "+s"(b)); return b; }
; DI void combine_phase(const Params& p, int layer) {
;     ...
;   {
;     const int tid = ltid(), lane = tid & 63, wid = tid >> 6;
;     const float* dl = p.dlam + layer * 128;
;     float a = 0.f, b = 0.f;
;     if (lane < 32) { a = dl[lane] * dl[32 + lane]; b = dl[64 + lane] * dl[96 + lane]; }
;     a = wave_sum(a);
;     b = wave_sum(b);
;     const float lam_init = 0.8f - 0.6f * expf(-0.3f * (float)layer);
;     const float lam = expf(a) - expf(b) + lam_init;
;     const int hs = lane >> 5, dq = lane & 31;
;     const int nch = hs ? NCH3 : NCH2;
;     const float g0 = p.subln[layer * 64 + 2 * dq], g1 = p.subln[layer * 64 + 2 * dq + 1];
;     for (int tok = lbid() * 8 + wid; tok < S; tok += gridDim.x * 8) {
;       const int qt = tok >> 8, r = tok & 255;
;       const int slot0 = hs ? (qt * NCH3) : (64 * NCH3 + qt * NCH2);
;       float o1a = 0.f, o1b = 0.f, o2a = 0.f, o2b = 0.f, l1 = 0.f, l2 = 0.f;
;       for (int c = 0; c < nch; ++c) {
;         const char* sl = p.ws + OFF_SPL + (size_t)(slot0 + c) * SLOT_BYTES;
;         const unsigned v1 = *(const unsigned*)(sl + r * 128 + dq * 4);
;         const unsigned v2 = *(const unsigned*)(sl + 32768 + r * 128 + dq * 4);
;         const float2 lv = *(const float2*)(sl + 65536 + r * 8);
.LBB0_280:
	s_or_b64 exec, exec, s[0:1]
	v_and_b32_e32 v6, 31, v5
	v_lshlrev_b32_e32 v0, 3, v6
	global_load_dwordx2 v[0:1], v0, s[20:21]
	v_cmp_lt_i32_e32 vcc, v159, v165
	v_ashrrev_i32_e32 v9, 6, v5
	s_mov_b32 s0, s92
	v_cndmask_b32_e32 v7, v164, v159, vcc
	v_lshlrev_b32_e32 v159, 2, v7
	ds_bpermute_b32 v7, v159, v3
	v_cmp_lt_i32_e32 vcc, v160, v165
	s_waitcnt lgkmcnt(0)
	v_add_f32_e32 v3, v3, v7
	v_cndmask_b32_e32 v7, v164, v160, vcc
	v_lshlrev_b32_e32 v160, 2, v7
	ds_bpermute_b32 v7, v160, v3
	v_cmp_lt_i32_e32 vcc, v161, v165
	v_lshl_add_u32 v10, s0, 3, v9
	s_movk_i32 s0, 0x4000
	s_waitcnt lgkmcnt(0)
	v_add_f32_e32 v3, v3, v7
	v_cndmask_b32_e32 v7, v164, v161, vcc
	v_lshlrev_b32_e32 v161, 2, v7
	ds_bpermute_b32 v7, v161, v3
	v_cmp_lt_i32_e32 vcc, v162, v165
	s_waitcnt lgkmcnt(0)
	v_add_f32_e32 v3, v3, v7
	ds_bpermute_b32 v7, v159, v2
	v_cndmask_b32_e32 v8, v164, v162, vcc
	v_lshlrev_b32_e32 v162, 2, v8
	ds_bpermute_b32 v8, v162, v3
	v_cmp_lt_i32_e32 vcc, v163, v165
	s_waitcnt lgkmcnt(1)
	v_add_f32_e32 v2, v2, v7
	ds_bpermute_b32 v7, v160, v2
	s_waitcnt lgkmcnt(1)
	v_add_f32_e32 v3, v3, v8
	v_cndmask_b32_e32 v8, v164, v163, vcc
	v_lshlrev_b32_e32 v163, 2, v8
	s_waitcnt lgkmcnt(0)
	v_add_f32_e32 v2, v2, v7
	ds_bpermute_b32 v7, v161, v2
	ds_bpermute_b32 v8, v163, v3
	v_cmp_lt_i32_e32 vcc, v166, v165
	s_waitcnt lgkmcnt(1)
	v_add_f32_e32 v2, v2, v7
	ds_bpermute_b32 v7, v162, v2
	s_waitcnt lgkmcnt(1)
	v_add_f32_e32 v5, v3, v8
	s_waitcnt lgkmcnt(0)
	v_add_f32_e32 v2, v2, v7
	ds_bpermute_b32 v3, v163, v2
	v_cndmask_b32_e32 v7, v164, v166, vcc
	v_lshlrev_b32_e32 v164, 2, v7
	ds_bpermute_b32 v7, v164, v5
	v_cmp_gt_i32_e32 vcc, s0, v10
	s_waitcnt lgkmcnt(1)
	v_add_f32_e32 v2, v2, v3
	ds_bpermute_b32 v3, v164, v2
	s_and_saveexec_b64 s[4:5], vcc
	s_cbranch_execz .LBB0_283
	s_waitcnt lgkmcnt(1)
	v_add_f32_e32 v5, v5, v7
	s_mov_b32 s0, 0x3fb8aa3b
	v_mul_f32_e32 v7, 0x3fb8aa3b, v5
	v_fma_f32 v8, v5, s0, -v7
	v_rndne_f32_e32 v9, v7
	v_fmac_f32_e32 v8, 0x32a5705f, v5
	v_sub_f32_e32 v7, v7, v9
	v_add_f32_e32 v7, v7, v8
	v_exp_f32_e32 v7, v7
	v_cvt_i32_f32_e32 v8, v9
	s_waitcnt lgkmcnt(0)
	v_add_f32_e32 v2, v2, v3
	s_mov_b32 s1, 0xc2ce8ed0
	v_cmp_ngt_f32_e32 vcc, s1, v5
	v_ldexp_f32 v3, v7, v8
	v_mul_f32_e32 v7, 0x3fb8aa3b, v2
	v_fma_f32 v8, v2, s0, -v7
	v_rndne_f32_e32 v11, v7
	v_fmac_f32_e32 v8, 0x32a5705f, v2
	v_sub_f32_e32 v7, v7, v11
	v_add_f32_e32 v7, v7, v8
	v_exp_f32_e32 v7, v7
	v_cvt_i32_f32_e32 v8, v11
	s_mov_b32 s6, 0x42b17218
	v_cndmask_b32_e32 v3, 0, v3, vcc
	v_mov_b32_e32 v11, 0x7f800000
	v_cmp_nlt_f32_e32 vcc, s6, v5
	v_ldexp_f32 v5, v7, v8
	v_lshlrev_b32_e32 v9, 1, v6
	v_cndmask_b32_e32 v3, v11, v3, vcc
	v_cmp_ngt_f32_e32 vcc, s1, v2
	v_and_b32_e32 v4, 0x80, v4
	s_lshl_b32 s10, s11, 3
	v_cndmask_b32_e32 v5, 0, v5, vcc
	v_cmp_nlt_f32_e32 vcc, s6, v2
	s_mov_b64 s[6:7], 0
	s_mov_b32 s30, 0x10800
	v_cndmask_b32_e32 v2, v11, v5, vcc
	v_sub_f32_e32 v2, v3, v2
	v_mov_b32_e32 v5, 0
	v_add_f32_e32 v11, 0x3e4ccccc, v2
	v_lshlrev_b32_e32 v2, 2, v6
	v_lshl_add_u64 v[6:7], s[26:27], 0, v[4:5]
	v_lshlrev_b32_e32 v4, 1, v9
	v_mov_b32_e32 v3, v5
	v_lshl_add_u64 v[6:7], v[6:7], 0, v[4:5]
	v_mov_b64_e32 v[8:9], s[16:17]
	s_mov_b32 s31, 0x8000
	s_mov_b32 s33, 0x10000
	v_mov_b32_e32 v12, 0x358637bd
	s_mov_b32 s34, 0x800000
	s_movk_i32 s35, 0x880
	s_movk_i32 s36, 0x3fff
	v_mov_b32_e32 v13, 7
	v_mov_b32_e32 v14, 3
	v_mov_b32_e32 v105, v5
	v_ashrrev_i32_e32 v115, 7, v10
	v_and_b32_e32 v115, -2, v115
	v_add_u32_e32 v118, 0x80, v115
	v_cndmask_b32_e64 v115, v115, v118, s[2:3]
	v_lshlrev_b32_sdwa v104, v13, v10 dst_sel:DWORD dst_unused:UNUSED_PAD src0_sel:DWORD src1_sel:BYTE_0
	s_nop 0
	v_mad_i64_i32 v[118:119], s[0:1], v115, s30, v[8:9]
	v_or_b32_e32 v115, 1, v115
	v_lshl_add_u64 v[120:121], v[118:119], 0, v[104:105]
	v_mad_i64_i32 v[122:123], s[0:1], v115, s30, v[8:9]
	v_lshl_add_u64 v[120:121], v[120:121], 0, v[2:3]
	v_lshlrev_b32_sdwa v116, v14, v10 dst_sel:DWORD dst_unused:UNUSED_PAD src0_sel:DWORD src1_sel:BYTE_0
	s_nop 0
	v_mov_b32_e32 v117, v105
	v_lshl_add_u64 v[124:125], v[122:123], 0, v[104:105]
	global_load_dword v104, v[120:121], off
	v_add_co_u32_e32 v120, vcc, 0x8000, v120
	v_lshl_add_u64 v[118:119], v[118:119], 0, v[116:117]
	s_nop 1
	v_addc_co_u32_e32 v121, vcc, 0, v121, vcc
	v_add_co_u32_e32 v118, vcc, 0x10000, v118
	v_lshl_add_u64 v[116:117], v[122:123], 0, v[116:117]
	v_lshl_add_u64 v[122:123], v[124:125], 0, v[2:3]
	s_nop 1
	v_addc_co_u32_e32 v119, vcc, 0, v119, vcc
	v_add_co_u32_e32 v124, vcc, s31, v122
	global_load_dword v115, v[120:121], off
	global_load_dwordx2 v[118:119], v[118:119], off
	global_load_dword v126, v[122:123], off
	s_nop 1
	v_addc_co_u32_e32 v125, vcc, 0, v123, vcc
	v_add_co_u32_e32 v116, vcc, s33, v116
	s_nop 1
	v_addc_co_u32_e32 v117, vcc, 0, v117, vcc
	global_load_dwordx2 v[116:117], v[116:117], off
	global_load_dword v125, v[124:125], off
	s_waitcnt vmcnt(0)
	s_branch .Lpl2_aw

; DI float bflo(unsigned u) { return __uint_as_float(u << 16); }
; DI float bfhi(unsigned u) { return __uint_as_float(u & 0xffff0000u); }
; DI int lbid() { int b = blockIdx.x; asm volatile("" : "+s"(b)); return b; }
; DI void combine_phase(const Params& p, int layer) {
;     ...
;     for (int tok = lbid() * 8 + wid; tok < S; tok += gridDim.x * 8) {
;       const int qt = tok >> 8, r = tok & 255;
;       const int slot0 = hs ? (qt * NCH3) : (64 * NCH3 + qt * NCH2);
;       float o1a = 0.f, o1b = 0.f, o2a = 0.f, o2b = 0.f, l1 = 0.f, l2 = 0.f;
;       for (int c = 0; c < nch; ++c) {
;         const char* sl = p.ws + OFF_SPL + (size_t)(slot0 + c) * SLOT_BYTES;
;         const unsigned v1 = *(const unsigned*)(sl + r * 128 + dq * 4);
;         const unsigned v2 = *(const unsigned*)(sl + 32768 + r * 128 + dq * 4);
;         const float2 lv = *(const float2*)(sl + 65536 + r * 8);
;         o1a += bflo(v1); o1b += bfhi(v1);
;         o2a += bflo(v2); o2b += bfhi(v2);
;         l1 += lv.x; l2 += lv.y;
;       }
;       const float i1 = 1.f / l1, i2 = lam / l2;
;       const float oa = o1a * i1 - o2a * i2, ob = o1b * i1 - o2b * i2;
;       float ss = oa * oa + ob * ob;
; #pragma unroll
;       for (int o = 1; o <= 16; o <<= 1) ss += __shfl_xor(ss, o);
;       const float rr = rsqrtf(ss * (1.f / 64.f) + EPS) * (1.f - lam_init);
;       *(unsigned*)(mixed + (size_t)tok * LDH + 384 + (2 + hs) * 64 + 2 * dq) = pack2(oa * rr * g0, ob * rr * g1);
.Lpl2_aw:
	v_ashrrev_i32_e32 v15, 7, v10
	v_and_b32_e32 v15, -2, v15
	v_add_u32_e32 v18, 0x80, v15
	v_cndmask_b32_e64 v15, v15, v18, s[2:3]
	v_lshlrev_b32_sdwa v4, v13, v10 dst_sel:DWORD dst_unused:UNUSED_PAD src0_sel:DWORD src1_sel:BYTE_0
	v_mad_i64_i32 v[18:19], s[0:1], v15, s30, v[8:9]
	v_or_b32_e32 v15, 1, v15
	v_lshl_add_u64 v[20:21], v[18:19], 0, v[4:5]
	v_mad_i64_i32 v[22:23], s[0:1], v15, s30, v[8:9]
	v_lshl_add_u64 v[20:21], v[20:21], 0, v[2:3]
	v_lshlrev_b32_sdwa v16, v14, v10 dst_sel:DWORD dst_unused:UNUSED_PAD src0_sel:DWORD src1_sel:BYTE_0
	v_mov_b32_e32 v17, v5
	v_lshl_add_u64 v[24:25], v[22:23], 0, v[4:5]
	v_mov_b32_e32 v4, v104
	v_add_co_u32_e32 v20, vcc, 0x8000, v20
	v_lshl_add_u64 v[18:19], v[18:19], 0, v[16:17]
	s_nop 0
	v_addc_co_u32_e32 v21, vcc, 0, v21, vcc
	v_add_co_u32_e32 v18, vcc, 0x10000, v18
	v_lshl_add_u64 v[16:17], v[22:23], 0, v[16:17]
	v_lshl_add_u64 v[22:23], v[24:25], 0, v[2:3]
	v_addc_co_u32_e32 v19, vcc, 0, v19, vcc
	v_add_co_u32_e32 v24, vcc, s31, v22
	v_mov_b32_e32 v15, v115
	s_nop 0
	v_mov_b64_e32 v[18:19], v[118:119]
	s_nop 0
	v_mov_b32_e32 v26, v126
	v_addc_co_u32_e32 v25, vcc, 0, v23, vcc
	v_add_co_u32_e32 v16, vcc, s33, v16
	v_lshlrev_b32_e32 v20, 16, v4
	v_addc_co_u32_e32 v17, vcc, 0, v17, vcc
	v_mov_b64_e32 v[16:17], v[116:117]
	s_nop 0
	v_mov_b32_e32 v25, v125
	v_and_b32_e32 v21, 0xffff0000, v4
	v_pk_add_f32 v[20:21], v[20:21], 0 op_sel_hi:[1,0]
	v_lshlrev_b32_e32 v22, 16, v15
	v_add_f32_e32 v4, 0, v18
	v_and_b32_e32 v23, 0xffff0000, v15
	v_add_f32_e32 v15, 0, v19
	v_lshlrev_b32_e32 v18, 16, v26
	v_and_b32_e32 v19, 0xffff0000, v26
	v_pk_add_f32 v[22:23], v[22:23], 0 op_sel_hi:[1,0]
	v_pk_add_f32 v[18:19], v[20:21], v[18:19]
	v_add_f32_e32 v4, v4, v16
	v_lshlrev_b32_e32 v24, 16, v25
	v_and_b32_e32 v25, 0xffff0000, v25
	v_add_f32_e32 v15, v15, v17
	v_div_scale_f32 v20, s[0:1], v4, v4, 1.0
	v_pk_add_f32 v[16:17], v[22:23], v[24:25]
	v_div_scale_f32 v22, s[0:1], v15, v15, v11
	v_rcp_f32_e32 v24, v20
	v_rcp_f32_e32 v25, v22
	v_div_scale_f32 v21, vcc, 1.0, v4, 1.0
	v_fma_f32 v26, -v20, v24, 1.0
	v_fma_f32 v27, -v22, v25, 1.0
	v_fmac_f32_e32 v24, v26, v24
	v_div_scale_f32 v23, s[0:1], v11, v15, v11
	v_fmac_f32_e32 v25, v27, v25
	v_mul_f32_e32 v26, v21, v24
	v_mul_f32_e32 v27, v23, v25
	v_fma_f32 v28, -v20, v26, v21
	v_fma_f32 v29, -v22, v27, v23
	v_fmac_f32_e32 v26, v28, v24
	v_fmac_f32_e32 v27, v29, v25
	v_fma_f32 v20, -v20, v26, v21
	v_fma_f32 v21, -v22, v27, v23
	v_div_fmas_f32 v20, v20, v24, v26
	s_mov_b64 vcc, s[0:1]
	v_div_fixup_f32 v4, v20, v4, 1.0
	v_div_fmas_f32 v20, v21, v25, v27
	v_div_fixup_f32 v20, v20, v15, v11
	v_pk_mul_f32 v[16:17], v[16:17], v[20:21] op_sel_hi:[1,0]
	s_nop 0
	v_pk_fma_f32 v[16:17], v[18:19], v[4:5], v[16:17] op_sel_hi:[1,0,1] neg_lo:[0,0,1] neg_hi:[0,0,1]
	s_nop 0
	v_pk_mul_f32 v[18:19], v[16:17], v[16:17]
	s_nop 0
	v_add_f32_e32 v4, v18, v19
	ds_bpermute_b32 v15, v164, v4
	v_mad_i64_i32 v[18:19], s[0:1], v10, s35, v[6:7]
	v_add_u32_e32 v10, s10, v10
	v_cmp_lt_i32_e64 s[0:1], s36, v10
	s_waitcnt lgkmcnt(0)
	v_add_f32_e32 v4, v4, v15
	ds_bpermute_b32 v15, v163, v4
	s_or_b64 s[6:7], s[0:1], s[6:7]
	s_mov_b64 s[98:99], exec
	s_andn2_b64 exec, exec, s[6:7]
	s_cbranch_execz .Lpl2_np
	v_mov_b32_e32 v105, v5
	v_ashrrev_i32_e32 v115, 7, v10
	v_and_b32_e32 v115, -2, v115
	v_add_u32_e32 v118, 0x80, v115
	v_cndmask_b32_e64 v115, v115, v118, s[2:3]
	v_lshlrev_b32_sdwa v104, v13, v10 dst_sel:DWORD dst_unused:UNUSED_PAD src0_sel:DWORD src1_sel:BYTE_0
	s_nop 0
	v_mad_i64_i32 v[118:119], s[0:1], v115, s30, v[8:9]
	v_or_b32_e32 v115, 1, v115
	v_lshl_add_u64 v[120:121], v[118:119], 0, v[104:105]
	v_mad_i64_i32 v[122:123], s[0:1], v115, s30, v[8:9]
	v_lshl_add_u64 v[120:121], v[120:121], 0, v[2:3]
	v_lshlrev_b32_sdwa v116, v14, v10 dst_sel:DWORD dst_unused:UNUSED_PAD src0_sel:DWORD src1_sel:BYTE_0
	s_nop 0
	v_mov_b32_e32 v117, v105
	v_lshl_add_u64 v[124:125], v[122:123], 0, v[104:105]
	global_load_dword v104, v[120:121], off
	v_add_co_u32_e32 v120, vcc, 0x8000, v120
	v_lshl_add_u64 v[118:119], v[118:119], 0, v[116:117]
	s_nop 1
	v_addc_co_u32_e32 v121, vcc, 0, v121, vcc
	v_add_co_u32_e32 v118, vcc, 0x10000, v118
	v_lshl_add_u64 v[116:117], v[122:123], 0, v[116:117]
	v_lshl_add_u64 v[122:123], v[124:125], 0, v[2:3]
	s_nop 1
	v_addc_co_u32_e32 v119, vcc, 0, v119, vcc
	v_add_co_u32_e32 v124, vcc, s31, v122
	global_load_dword v115, v[120:121], off
	global_load_dwordx2 v[118:119], v[118:119], off
	global_load_dword v126, v[122:123], off
	s_nop 1
	v_addc_co_u32_e32 v125, vcc, 0, v123, vcc
	v_add_co_u32_e32 v116, vcc, s33, v116
	s_nop 1
	v_addc_co_u32_e32 v117, vcc, 0, v117, vcc
	global_load_dwordx2 v[116:117], v[116:117], off
	global_load_dword v125, v[124:125], off
.Lpl2_np:
	s_mov_b64 exec, s[98:99]
	s_waitcnt lgkmcnt(0)
	v_add_f32_e32 v4, v4, v15
	ds_bpermute_b32 v15, v162, v4
	s_waitcnt lgkmcnt(0)
	v_add_f32_e32 v4, v4, v15
	ds_bpermute_b32 v15, v161, v4
	s_waitcnt lgkmcnt(0)
	v_add_f32_e32 v4, v4, v15
	ds_bpermute_b32 v15, v160, v4
	s_waitcnt lgkmcnt(0)
	v_add_f32_e32 v4, v4, v15
	v_fmamk_f32 v4, v4, 0x3c800000, v12
	v_mul_f32_e32 v15, 0x4b800000, v4
	v_cmp_gt_f32_e32 vcc, s34, v4
	s_nop 1
	v_cndmask_b32_e32 v4, v4, v15, vcc
	v_rsq_f32_e32 v4, v4
	s_nop 0
	v_mul_f32_e32 v15, 0x45800000, v4
	v_cndmask_b32_e32 v4, v4, v15, vcc
	v_mul_f32_e32 v4, 0x3f4ccccd, v4
	v_pk_mul_f32 v[16:17], v[16:17], v[4:5] op_sel_hi:[1,0]
	s_nop 0
	v_pk_mul_f32 v[16:17], v[0:1], v[16:17]
	s_nop 0
	v_cvt_pk_bf16_f32 v4, v16, v17
	global_store_dword v[18:19], v4, off offset:1024
	s_andn2_b64 exec, exec, s[6:7]
	s_cbranch_execnz .Lpl2_top

; #define PG8_STAGE(bufoff, gbase, voff) do { _Pragma("unroll") for (int _i = 0; _i < 2; ++_i) \
;         __builtin_amdgcn_global_load_lds((const unsigned*)((const char*)(gbase) + (voff)[_i]), (PG8_LAS unsigned*)(lds + (bufoff) + ldsw + _i * 8192), 16, 0, 0); } while (0)
; #define PG8_LDA(dst, b, h) do { _Pragma("unroll") for (int m = 0; m < 4; ++m) _Pragma("unroll") for (int k = 0; k < 2; ++k) dst[m][k] = *(const PG8_LAS bf16x8*)(lds + PG8_SA(b, h) + aoff + m * 2048 + k * 1024); } while (0)
; template <class Epi, class Sched, bool STAMP = false>
; __device__ __forceinline__ void gemm_phase(PG8_LAS unsigned char* lds, const Gemm g, const Sched& S, const Epi& E, unsigned long long* stamps) {
;     ...
;         for (int t = 0; t < nt; t += 2) {
;             const bool last = (t == nt - 2);
;             const char* a1 = cA + (size_t)(t + 1) * kstep;
;             const char* a2 = last ? nA : cA + (size_t)(t + 2) * kstep; const char* b2 = last ? nB : cB + (size_t)(t + 2) * kstep;
;             const char* a3 = a2 + kstep; const char* b3 = b2 + kstep;
;             if (last && has_next) S.a_ready(nxt);
;             PG8_LDB(B0, 0, 0); PG8_SCHED; PG8_LDA(At, 0, 0); PG8_STAGE(PG8_SA(1, 1), a1 + hstep, voffA);
;             PG8_WAIT_L(8); PG8_BAR; PG8_WAIT_L(0); PG8_MMA(0, 0, At, B0); PG8_BAR; PG8_SCHED;
;             PG8_LDB(B1, 0, 1); PG8_STAGE(PG8_SB(0, 0), b2, voffB);
;             PG8_BAR; PG8_WAIT_L(0); PG8_MMA(0, 1, At, B1); PG8_BAR;
;             PG8_LDA(At, 0, 1); PG8_STAGE(PG8_SA(0, 0), a2, voffA);
;             PG8_BAR; PG8_WAIT_L(0); PG8_MMA(1, 0, At, B0); PG8_BAR; PG8_SCHED;
;             PG8_STAGE(PG8_SB(0, 1), b2 + hstep, voffB);
;             PG8_WAIT_V(6); PG8_BAR; PG8_MMA(1, 1, At, B1); PG8_BAR;
;             PG8_LDB(B0, 1, 0); PG8_SCHED; PG8_LDA(At, 1, 0); PG8_STAGE(PG8_SA(0, 1), a2 + hstep, voffA);
;             PG8_WAIT_L(8); PG8_BAR; PG8_WAIT_L(0); PG8_MMA(0, 0, At, B0); PG8_BAR; PG8_SCHED;
;             PG8_LDB(B1, 1, 1); PG8_STAGE(PG8_SB(1, 0), b3, voffB);
;             PG8_BAR; PG8_WAIT_L(0); PG8_MMA(0, 1, At, B1); PG8_BAR;
;             PG8_LDA(At, 1, 1); PG8_STAGE(PG8_SA(1, 0), a3, voffA);
;             PG8_BAR; PG8_WAIT_L(0); PG8_MMA(1, 0, At, B0); PG8_BAR; PG8_SCHED;
;             PG8_STAGE(PG8_SB(1, 1), b3 + hstep, voffB);
;             PG8_WAIT_V(6); PG8_BAR; PG8_MMA(1, 1, At, B1); PG8_BAR;
;         }
.Lgu2_half_loop:
	ds_read_b128 v[140:143], v147
	ds_read_b128 v[170:173], v148
	ds_read_b128 v[174:177], v149
	ds_read_b128 v[178:181], v150
	s_add_u32 s36, s34, 0x100
	s_addc_u32 s37, s35, 0
	s_cmp_eq_u32 s89, 12
	s_cselect_b32 s55, s5, s37
	s_cselect_b32 s54, s4, s36
	s_cselect_b32 s53, s1, s88
	s_cselect_b32 s52, s0, s87
	s_mov_b32 m0, s78
	ds_read_b128 v[182:185], v145
	ds_read_b128 v[186:189], v145 offset:1024
	ds_read_b128 v[190:193], v145 offset:2048
	ds_read_b128 v[194:197], v145 offset:3072
	ds_read_b128 v[198:201], v145 offset:4096
	ds_read_b128 v[202:205], v145 offset:5120
	ds_read_b128 v[206:209], v145 offset:6144
	ds_read_b128 v[210:213], v145 offset:7168
	global_load_lds_dwordx4 v132, s[34:35]
	s_mov_b32 m0, s79
	s_nop 0
	global_load_lds_dwordx4 v134, s[34:35]
	s_waitcnt lgkmcnt(8)
	s_barrier
	s_waitcnt lgkmcnt(0)
	s_setprio 1
	s_waitcnt lgkmcnt(0)
	v_mfma_f32_16x16x32_bf16 v[124:127], v[140:143], v[182:185], v[124:127]
	v_mfma_f32_16x16x32_bf16 v[120:123], v[174:177], v[182:185], v[120:123]
	v_mfma_f32_16x16x32_bf16 v[108:111], v[140:143], v[190:193], v[108:111]
	v_mfma_f32_16x16x32_bf16 v[104:107], v[174:177], v[190:193], v[104:107]
	v_mfma_f32_16x16x32_bf16 v[92:95], v[140:143], v[198:201], v[92:95]
	v_mfma_f32_16x16x32_bf16 v[88:91], v[174:177], v[198:201], v[88:91]
	v_mfma_f32_16x16x32_bf16 v[76:79], v[140:143], v[206:209], v[76:79]
	v_mfma_f32_16x16x32_bf16 v[72:75], v[174:177], v[206:209], v[72:75]
	v_mfma_f32_16x16x32_bf16 v[124:127], v[170:173], v[186:189], v[124:127]
	v_mfma_f32_16x16x32_bf16 v[120:123], v[178:181], v[186:189], v[120:123]
	v_mfma_f32_16x16x32_bf16 v[108:111], v[170:173], v[194:197], v[108:111]
	v_mfma_f32_16x16x32_bf16 v[104:107], v[178:181], v[194:197], v[104:107]
	v_mfma_f32_16x16x32_bf16 v[92:95], v[170:173], v[202:205], v[92:95]
	v_mfma_f32_16x16x32_bf16 v[88:91], v[178:181], v[202:205], v[88:91]
	v_mfma_f32_16x16x32_bf16 v[76:79], v[170:173], v[210:213], v[76:79]
	v_mfma_f32_16x16x32_bf16 v[72:75], v[178:181], v[210:213], v[72:75]
	s_setprio 0
	s_barrier
	s_mov_b32 m0, s61
	s_nop 0
	global_load_lds_dwordx4 v130, s[52:53]
	s_mov_b32 m0, s62
	s_nop 0
	global_load_lds_dwordx4 v128, s[52:53]
	s_barrier
	s_waitcnt lgkmcnt(0)
	s_setprio 1
	s_waitcnt lgkmcnt(0)
	s_setprio 0
	s_mov_b32 m0, s58
	s_barrier
	ds_read_b128 v[182:185], v145 offset:16384
	ds_read_b128 v[186:189], v145 offset:17408
	ds_read_b128 v[190:193], v145 offset:18432
	ds_read_b128 v[194:197], v145 offset:19456
	ds_read_b128 v[198:201], v145 offset:20480
	ds_read_b128 v[202:205], v145 offset:21504
	ds_read_b128 v[206:209], v145 offset:22528
	ds_read_b128 v[210:213], v145 offset:23552
	global_load_lds_dwordx4 v130, s[54:55]
	s_mov_b32 m0, s63
	s_nop 0
	global_load_lds_dwordx4 v128, s[54:55]
	s_barrier
	s_waitcnt lgkmcnt(0)
	s_setprio 1
	s_waitcnt lgkmcnt(0)
	v_mfma_f32_16x16x32_bf16 v[60:63], v[140:143], v[182:185], v[60:63]
	v_mfma_f32_16x16x32_bf16 v[56:59], v[174:177], v[182:185], v[56:59]
	v_mfma_f32_16x16x32_bf16 v[44:47], v[140:143], v[190:193], v[44:47]
	v_mfma_f32_16x16x32_bf16 v[40:43], v[174:177], v[190:193], v[40:43]
	v_mfma_f32_16x16x32_bf16 v[28:31], v[140:143], v[198:201], v[28:31]
	v_mfma_f32_16x16x32_bf16 v[24:27], v[174:177], v[198:201], v[24:27]
	v_mfma_f32_16x16x32_bf16 v[12:15], v[140:143], v[206:209], v[12:15]
	v_mfma_f32_16x16x32_bf16 v[8:11], v[174:177], v[206:209], v[8:11]
	v_mfma_f32_16x16x32_bf16 v[60:63], v[170:173], v[186:189], v[60:63]
	v_mfma_f32_16x16x32_bf16 v[56:59], v[178:181], v[186:189], v[56:59]
	v_mfma_f32_16x16x32_bf16 v[44:47], v[170:173], v[194:197], v[44:47]
	v_mfma_f32_16x16x32_bf16 v[40:43], v[178:181], v[194:197], v[40:43]
	v_mfma_f32_16x16x32_bf16 v[28:31], v[170:173], v[202:205], v[28:31]
	v_mfma_f32_16x16x32_bf16 v[24:27], v[178:181], v[202:205], v[24:27]
	v_mfma_f32_16x16x32_bf16 v[12:15], v[170:173], v[210:213], v[12:15]
	v_mfma_f32_16x16x32_bf16 v[8:11], v[178:181], v[210:213], v[8:11]
	s_setprio 0
	s_barrier
	s_add_u32 s34, s52, 0x44000
	s_addc_u32 s35, s53, 0
	s_mov_b32 m0, s64
	s_nop 0
	s_mov_b32 m0, s65
	s_nop 0
	s_waitcnt vmcnt(4)
	s_barrier
	s_setprio 1
	s_setprio 0
	s_barrier
	ds_read_b128 v[140:143], v155
	ds_read_b128 v[170:173], v156
	ds_read_b128 v[174:177], v157
	ds_read_b128 v[178:181], v165
	s_add_u32 s34, s54, 0x44000
	s_addc_u32 s35, s55, 0
	s_mov_b32 m0, s66
	ds_read_b128 v[182:185], v145 offset:32768
	ds_read_b128 v[186:189], v145 offset:33792
	ds_read_b128 v[190:193], v145 offset:34816
	ds_read_b128 v[194:197], v145 offset:35840
	ds_read_b128 v[198:201], v145 offset:36864
	ds_read_b128 v[202:205], v145 offset:37888
	ds_read_b128 v[206:209], v145 offset:38912
	ds_read_b128 v[210:213], v145 offset:39936
	global_load_lds_dwordx4 v130, s[34:35]
	s_mov_b32 m0, s67
	s_nop 0
	global_load_lds_dwordx4 v128, s[34:35]
	s_waitcnt lgkmcnt(8)
	s_barrier
	s_waitcnt lgkmcnt(0)
	s_setprio 1
	s_waitcnt lgkmcnt(0)
	v_mfma_f32_16x16x32_bf16 v[124:127], v[140:143], v[182:185], v[124:127]
	v_mfma_f32_16x16x32_bf16 v[120:123], v[174:177], v[182:185], v[120:123]
	v_mfma_f32_16x16x32_bf16 v[108:111], v[140:143], v[190:193], v[108:111]
	v_mfma_f32_16x16x32_bf16 v[104:107], v[174:177], v[190:193], v[104:107]
	v_mfma_f32_16x16x32_bf16 v[92:95], v[140:143], v[198:201], v[92:95]
	v_mfma_f32_16x16x32_bf16 v[88:91], v[174:177], v[198:201], v[88:91]
	v_mfma_f32_16x16x32_bf16 v[76:79], v[140:143], v[206:209], v[76:79]
	v_mfma_f32_16x16x32_bf16 v[72:75], v[174:177], v[206:209], v[72:75]
	v_mfma_f32_16x16x32_bf16 v[124:127], v[170:173], v[186:189], v[124:127]
	v_mfma_f32_16x16x32_bf16 v[120:123], v[178:181], v[186:189], v[120:123]
	v_mfma_f32_16x16x32_bf16 v[108:111], v[170:173], v[194:197], v[108:111]
	v_mfma_f32_16x16x32_bf16 v[104:107], v[178:181], v[194:197], v[104:107]
	v_mfma_f32_16x16x32_bf16 v[92:95], v[170:173], v[202:205], v[92:95]
	v_mfma_f32_16x16x32_bf16 v[88:91], v[178:181], v[202:205], v[88:91]
	v_mfma_f32_16x16x32_bf16 v[76:79], v[170:173], v[210:213], v[76:79]
	v_mfma_f32_16x16x32_bf16 v[72:75], v[178:181], v[210:213], v[72:75]
	s_setprio 0
	s_barrier
; #define PG8_STAGE(bufoff, gbase, voff) do { _Pragma("unroll") for (int _i = 0; _i < 2; ++_i) \
;         __builtin_amdgcn_global_load_lds((const unsigned*)((const char*)(gbase) + (voff)[_i]), (PG8_LAS unsigned*)(lds + (bufoff) + ldsw + _i * 8192), 16, 0, 0); } while (0)
; #define PG8_LDA(dst, b, h) do { _Pragma("unroll") for (int m = 0; m < 4; ++m) _Pragma("unroll") for (int k = 0; k < 2; ++k) dst[m][k] = *(const PG8_LAS bf16x8*)(lds + PG8_SA(b, h) + aoff + m * 2048 + k * 1024); } while (0)
; #define PG8_LDB(dst, b, h) do { _Pragma("unroll") for (int n = 0; n < 2; ++n) _Pragma("unroll") for (int k = 0; k < 2; ++k) dst[n][k] = *(const PG8_LAS bf16x8*)(lds + PG8_SB(b, h) + boff + n * 2048 + k * 1024); } while (0)
; #define PG8_MMA(ai, bj, At, Bt) do { __builtin_amdgcn_s_setprio(1); _Pragma("unroll") for (int m = 0; m < 4; ++m) _Pragma("unroll") for (int n = 0; n < 2; ++n) _Pragma("unroll") for (int k = 0; k < 2; ++k) \
;         acc[ai][bj][m][n] = __builtin_amdgcn_mfma_f32_16x16x32_bf16(Bt[n][k], At[m][k], acc[ai][bj][m][n], 0, 0, 0); __builtin_amdgcn_s_setprio(0); } while (0)
; #define PG8_WAIT_V(n) asm volatile("s_waitcnt vmcnt(" #n ")" ::: "memory")
; #define PG8_WAIT_L(n) asm volatile("s_waitcnt lgkmcnt(" #n ")" ::: "memory")
; #define PG8_BAR __builtin_amdgcn_s_barrier()
; #define PG8_SCHED __builtin_amdgcn_sched_barrier(0)
; template <class Epi, class Sched, bool STAMP = false>
; __device__ __forceinline__ void gemm_phase(PG8_LAS unsigned char* lds, const Gemm g, const Sched& S, const Epi& E, unsigned long long* stamps) {
;     ...
;             PG8_LDB(B0, 1, 0); PG8_SCHED; PG8_LDA(At, 1, 0); PG8_STAGE(PG8_SA(0, 1), a2 + hstep, voffA);
;             PG8_WAIT_L(8); PG8_BAR; PG8_WAIT_L(0); PG8_MMA(0, 0, At, B0); PG8_BAR; PG8_SCHED;
;             PG8_LDB(B1, 1, 1); PG8_STAGE(PG8_SB(1, 0), b3, voffB);
;             PG8_BAR; PG8_WAIT_L(0); PG8_MMA(0, 1, At, B1); PG8_BAR;
;             PG8_LDA(At, 1, 1); PG8_STAGE(PG8_SA(1, 0), a3, voffA);
;             PG8_BAR; PG8_WAIT_L(0); PG8_MMA(1, 0, At, B0); PG8_BAR; PG8_SCHED;
;             PG8_STAGE(PG8_SB(1, 1), b3 + hstep, voffB);
;             PG8_WAIT_V(6); PG8_BAR; PG8_MMA(1, 1, At, B1); PG8_BAR;
;         }
	s_mov_b32 m0, s70
	s_add_u32 s100, s52, 0x80
	s_addc_u32 s101, s53, 0
	global_load_lds_dwordx4 v130, s[100:101]
	s_mov_b32 m0, s71
	s_nop 0
	global_load_lds_dwordx4 v128, s[100:101]
	s_barrier
	s_waitcnt lgkmcnt(0)
	s_setprio 1
	s_waitcnt lgkmcnt(0)
	s_setprio 0
	s_mov_b32 m0, s73
	s_barrier
	ds_read_b128 v[182:185], v145 offset:49152
	ds_read_b128 v[186:189], v145 offset:50176
	ds_read_b128 v[190:193], v145 offset:51200
	ds_read_b128 v[194:197], v145 offset:52224
	ds_read_b128 v[198:201], v145 offset:53248
	ds_read_b128 v[202:205], v145 offset:54272
	ds_read_b128 v[206:209], v145 offset:55296
	ds_read_b128 v[210:213], v145 offset:56320
	s_add_u32 s100, s54, 0x80
	s_addc_u32 s101, s55, 0
	global_load_lds_dwordx4 v130, s[100:101]
	s_mov_b32 m0, s74
	s_nop 0
	global_load_lds_dwordx4 v128, s[100:101]
	s_barrier
	s_waitcnt lgkmcnt(0)
	s_setprio 1
	s_waitcnt lgkmcnt(0)
	v_mfma_f32_16x16x32_bf16 v[60:63], v[140:143], v[182:185], v[60:63]
	v_mfma_f32_16x16x32_bf16 v[56:59], v[174:177], v[182:185], v[56:59]
	v_mfma_f32_16x16x32_bf16 v[44:47], v[140:143], v[190:193], v[44:47]
	v_mfma_f32_16x16x32_bf16 v[40:43], v[174:177], v[190:193], v[40:43]
	v_mfma_f32_16x16x32_bf16 v[28:31], v[140:143], v[198:201], v[28:31]
	v_mfma_f32_16x16x32_bf16 v[24:27], v[174:177], v[198:201], v[24:27]
	v_mfma_f32_16x16x32_bf16 v[12:15], v[140:143], v[206:209], v[12:15]
	v_mfma_f32_16x16x32_bf16 v[8:11], v[174:177], v[206:209], v[8:11]
	v_mfma_f32_16x16x32_bf16 v[60:63], v[170:173], v[186:189], v[60:63]
	v_mfma_f32_16x16x32_bf16 v[56:59], v[178:181], v[186:189], v[56:59]
	v_mfma_f32_16x16x32_bf16 v[44:47], v[170:173], v[194:197], v[44:47]
	v_mfma_f32_16x16x32_bf16 v[40:43], v[178:181], v[194:197], v[40:43]
	v_mfma_f32_16x16x32_bf16 v[28:31], v[170:173], v[202:205], v[28:31]
	v_mfma_f32_16x16x32_bf16 v[24:27], v[178:181], v[202:205], v[24:27]
	v_mfma_f32_16x16x32_bf16 v[12:15], v[170:173], v[210:213], v[12:15]
	v_mfma_f32_16x16x32_bf16 v[8:11], v[178:181], v[210:213], v[8:11]
	s_setprio 0
	s_barrier
	s_add_u32 s34, s52, 0x44080
	s_addc_u32 s35, s53, 0
	s_mov_b32 m0, s75
	s_nop 0
	s_mov_b32 m0, s76
	s_nop 0
	s_waitcnt vmcnt(4)
	s_barrier
	s_setprio 1
	s_setprio 0
	s_add_i32 s89, s89, 2
	s_add_u32 s87, s87, 0x100
	s_addc_u32 s88, s88, 0
	s_cmp_gt_u32 s89, 13
	s_mov_b64 s[34:35], s[36:37]
	s_barrier
	s_cbranch_scc0 .Lgu2_half_loop
; DI float ex2(float x) { return __builtin_amdgcn_exp2f(x); }
;     DI void operator()(const f32x4 (&acc)[2][2][4][2], const Unit& u, int wr, int wc, int fr, int fq) const {
;         const int row0 = u.pm * BM + wr * 64 + fr, hcol0 = ((u.pn * BM + wc * 32) >> 1) + 4 * fq;
; #pragma unroll
;         for (int ai = 0; ai < 2; ++ai)
; #pragma unroll
;             for (int m = 0; m < 4; ++m) { u16* rowp = O + (size_t)(row0 + ai * HALF + m * 16) * ldc + hcol0;
; #pragma unroll
;                 for (int bj = 0; bj < 2; ++bj) { const f32x4 g = acc[ai][bj][m][0], up = acc[ai][bj][m][1]; float r[4];
; #pragma unroll
;                     for (int j = 0; j < 4; ++j) r[j] = g[j] * up[j] * __builtin_amdgcn_rcpf(1.f + ex2(-LOG2E * g[j]));
;                     uint2 w = {pack2(r[0], r[1]), pack2(r[2], r[3])}; *(uint2*)(rowp + bj * (HALF / 2)) = w; } }
;     }
	v_exp_f32_e64 v171, -v124
	v_exp_f32_e64 v175, -v125
	s_lshl_b32 s10, s86, 8
	v_add_f32_e32 v171, 1.0, v171
	v_rcp_f32_e32 v174, v171
	v_add_f32_e32 v171, 1.0, v175
	v_exp_f32_e64 v176, -v126
	v_exp_f32_e64 v177, -v127
	v_rcp_f32_e32 v175, v171
	v_add_f32_e32 v171, 1.0, v176
	v_rcp_f32_e32 v176, v171
	v_add_f32_e32 v171, 1.0, v177
	v_rcp_f32_e32 v177, v171
	v_pk_mul_f32 v[122:123], v[126:127], v[122:123]
	v_pk_mul_f32 v[120:121], v[124:125], v[120:121]
	s_or_b32 s10, s10, s69
	s_or_b32 s10, s10, s98
	v_pk_mul_f32 v[120:121], v[120:121], v[174:175]
	v_pk_mul_f32 v[122:123], v[122:123], v[176:177]
	s_ashr_i32 s10, s10, 1
	v_cvt_pk_bf16_f32 v120, v120, v121
	v_cvt_pk_bf16_f32 v121, v122, v123
	v_or_b32_e32 v140, s10, v146
	v_lshl_add_u32 v170, s85, 8, v144
	v_ashrrev_i32_e32 v141, 31, v140
	v_mov_b64_e32 v[142:143], s[12:13]
	v_mad_i64_i32 v[172:173], s[34:35], v170, s82, v[142:143]
	v_lshlrev_b64 v[140:141], 1, v[140:141]
	v_lshl_add_u64 v[172:173], v[172:173], 0, v[140:141]
	global_store_dwordx2 v[172:173], v[120:121], off
	v_exp_f32_e64 v114, -v108
	v_exp_f32_e64 v115, -v109
	v_exp_f32_e64 v116, -v110
	v_exp_f32_e64 v117, -v111
	v_add_f32_e32 v114, 1.0, v114
	v_add_f32_e32 v115, 1.0, v115
	v_add_f32_e32 v116, 1.0, v116
	v_add_f32_e32 v117, 1.0, v117
	v_rcp_f32_e32 v114, v114
	v_rcp_f32_e32 v115, v115
	v_rcp_f32_e32 v116, v116
	v_rcp_f32_e32 v117, v117
	v_pk_mul_f32 v[106:107], v[110:111], v[106:107]
	v_pk_mul_f32 v[104:105], v[108:109], v[104:105]
	v_pk_mul_f32 v[104:105], v[104:105], v[114:115]
	v_pk_mul_f32 v[106:107], v[106:107], v[116:117]
	v_cvt_pk_bf16_f32 v104, v104, v105
	v_cvt_pk_bf16_f32 v105, v106, v107
	v_or_b32_e32 v112, 16, v170
	v_mad_i64_i32 v[112:113], s[34:35], v112, s82, v[142:143]
	v_lshl_add_u64 v[112:113], v[112:113], 0, v[140:141]
	global_store_dwordx2 v[112:113], v[104:105], off
	v_exp_f32_e64 v98, -v92
	v_exp_f32_e64 v99, -v93
	v_exp_f32_e64 v100, -v94
	v_exp_f32_e64 v101, -v95
	v_add_f32_e32 v98, 1.0, v98
	v_add_f32_e32 v99, 1.0, v99
	v_add_f32_e32 v100, 1.0, v100
	v_add_f32_e32 v101, 1.0, v101
	v_rcp_f32_e32 v98, v98
	v_rcp_f32_e32 v99, v99
	v_rcp_f32_e32 v100, v100
	v_rcp_f32_e32 v101, v101
	v_pk_mul_f32 v[90:91], v[94:95], v[90:91]
	v_pk_mul_f32 v[88:89], v[92:93], v[88:89]
	v_pk_mul_f32 v[88:89], v[88:89], v[98:99]
	v_pk_mul_f32 v[90:91], v[90:91], v[100:101]
	v_cvt_pk_bf16_f32 v88, v88, v89
	v_cvt_pk_bf16_f32 v89, v90, v91
	v_or_b32_e32 v96, 32, v170
	v_mad_i64_i32 v[96:97], s[34:35], v96, s82, v[142:143]
	v_lshl_add_u64 v[96:97], v[96:97], 0, v[140:141]
	global_store_dwordx2 v[96:97], v[88:89], off
	v_exp_f32_e64 v82, -v76
	v_exp_f32_e64 v83, -v77
	v_exp_f32_e64 v84, -v78
	v_exp_f32_e64 v85, -v79
	v_add_f32_e32 v82, 1.0, v82
	v_add_f32_e32 v83, 1.0, v83
	v_add_f32_e32 v84, 1.0, v84
	v_add_f32_e32 v85, 1.0, v85
	v_rcp_f32_e32 v82, v82
	v_rcp_f32_e32 v83, v83
	v_rcp_f32_e32 v84, v84
	v_rcp_f32_e32 v85, v85
	v_pk_mul_f32 v[74:75], v[78:79], v[74:75]
	v_pk_mul_f32 v[72:73], v[76:77], v[72:73]
	v_pk_mul_f32 v[72:73], v[72:73], v[82:83]
	v_pk_mul_f32 v[74:75], v[74:75], v[84:85]
	v_cvt_pk_bf16_f32 v72, v72, v73
	v_cvt_pk_bf16_f32 v73, v74, v75
	v_or_b32_e32 v80, 48, v170
	v_mad_i64_i32 v[80:81], s[34:35], v80, s82, v[142:143]
	v_lshl_add_u64 v[80:81], v[80:81], 0, v[140:141]
	global_store_dwordx2 v[80:81], v[72:73], off
	v_exp_f32_e64 v66, -v60
	v_exp_f32_e64 v67, -v61
	v_exp_f32_e64 v68, -v62
	v_exp_f32_e64 v69, -v63
	v_add_f32_e32 v66, 1.0, v66
	v_add_f32_e32 v67, 1.0, v67
	v_add_f32_e32 v68, 1.0, v68
	v_add_f32_e32 v69, 1.0, v69
	v_rcp_f32_e32 v66, v66
	v_rcp_f32_e32 v67, v67
	v_rcp_f32_e32 v68, v68
	v_rcp_f32_e32 v69, v69
	v_pk_mul_f32 v[58:59], v[62:63], v[58:59]
	v_pk_mul_f32 v[56:57], v[60:61], v[56:57]
	v_pk_mul_f32 v[56:57], v[56:57], v[66:67]
	v_pk_mul_f32 v[58:59], v[58:59], v[68:69]
	v_cvt_pk_bf16_f32 v56, v56, v57
	v_cvt_pk_bf16_f32 v57, v58, v59
	v_add_u32_e32 v64, 0x80, v170
	v_mad_i64_i32 v[64:65], s[34:35], v64, s82, v[142:143]
	v_lshl_add_u64 v[64:65], v[64:65], 0, v[140:141]
	global_store_dwordx2 v[64:65], v[56:57], off
	v_exp_f32_e64 v50, -v44
	v_exp_f32_e64 v51, -v45
	v_exp_f32_e64 v52, -v46
	v_exp_f32_e64 v53, -v47
	v_add_f32_e32 v50, 1.0, v50
	v_add_f32_e32 v51, 1.0, v51
	v_add_f32_e32 v52, 1.0, v52
	v_add_f32_e32 v53, 1.0, v53
	v_rcp_f32_e32 v50, v50
	v_rcp_f32_e32 v51, v51
	v_rcp_f32_e32 v52, v52
	v_rcp_f32_e32 v53, v53
	v_pk_mul_f32 v[42:43], v[46:47], v[42:43]
	v_pk_mul_f32 v[40:41], v[44:45], v[40:41]
	v_pk_mul_f32 v[40:41], v[40:41], v[50:51]
	v_pk_mul_f32 v[42:43], v[42:43], v[52:53]
	v_cvt_pk_bf16_f32 v40, v40, v41
	v_cvt_pk_bf16_f32 v41, v42, v43
	v_add_u32_e32 v48, 0x90, v170
	v_mad_i64_i32 v[48:49], s[34:35], v48, s82, v[142:143]
	v_lshl_add_u64 v[48:49], v[48:49], 0, v[140:141]
	global_store_dwordx2 v[48:49], v[40:41], off
	v_exp_f32_e64 v34, -v28
	v_exp_f32_e64 v35, -v29
	v_exp_f32_e64 v36, -v30
	v_exp_f32_e64 v37, -v31
	v_add_f32_e32 v34, 1.0, v34
	v_add_f32_e32 v35, 1.0, v35
	v_add_f32_e32 v36, 1.0, v36
	v_add_f32_e32 v37, 1.0, v37
	v_rcp_f32_e32 v34, v34
	v_rcp_f32_e32 v35, v35
	v_rcp_f32_e32 v36, v36
	v_rcp_f32_e32 v37, v37
	v_pk_mul_f32 v[26:27], v[30:31], v[26:27]
	v_pk_mul_f32 v[24:25], v[28:29], v[24:25]
	v_pk_mul_f32 v[24:25], v[24:25], v[34:35]
	v_pk_mul_f32 v[26:27], v[26:27], v[36:37]
	v_cvt_pk_bf16_f32 v24, v24, v25
	v_cvt_pk_bf16_f32 v25, v26, v27
	v_add_u32_e32 v32, 0xa0, v170
	v_mad_i64_i32 v[32:33], s[34:35], v32, s82, v[142:143]
	v_lshl_add_u64 v[32:33], v[32:33], 0, v[140:141]
	global_store_dwordx2 v[32:33], v[24:25], off
	v_exp_f32_e64 v18, -v12
	v_exp_f32_e64 v19, -v13
	v_exp_f32_e64 v20, -v14
	v_exp_f32_e64 v21, -v15
	v_add_f32_e32 v18, 1.0, v18
	v_add_f32_e32 v19, 1.0, v19
	v_add_f32_e32 v20, 1.0, v20
	v_add_f32_e32 v21, 1.0, v21
	v_rcp_f32_e32 v18, v18
	v_rcp_f32_e32 v19, v19
	v_rcp_f32_e32 v20, v20
	v_rcp_f32_e32 v21, v21
	v_pk_mul_f32 v[10:11], v[14:15], v[10:11]
	v_pk_mul_f32 v[8:9], v[12:13], v[8:9]
	v_pk_mul_f32 v[8:9], v[8:9], v[18:19]
	v_pk_mul_f32 v[10:11], v[10:11], v[20:21]
	v_cvt_pk_bf16_f32 v8, v8, v9
	v_cvt_pk_bf16_f32 v9, v10, v11
	v_add_u32_e32 v16, 0xb0, v170
	v_mad_i64_i32 v[16:17], s[34:35], v16, s82, v[142:143]
	v_lshl_add_u64 v[16:17], v[16:17], 0, v[140:141]
	global_store_dwordx2 v[16:17], v[8:9], off
	s_and_b64 vcc, exec, s[2:3]
	s_mov_b32 s86, s83
	s_mov_b32 s85, s84
	s_mov_b64 s[36:37], s[0:1]
	s_mov_b64 s[34:35], s[4:5]

; #define PG8_STAGE(bufoff, gbase, voff) do { _Pragma("unroll") for (int _i = 0; _i < 2; ++_i) \
;         __builtin_amdgcn_global_load_lds((const unsigned*)((const char*)(gbase) + (voff)[_i]), (PG8_LAS unsigned*)(lds + (bufoff) + ldsw + _i * 8192), 16, 0, 0); } while (0)
; #define PG8_LDA(dst, b, h) do { _Pragma("unroll") for (int m = 0; m < 4; ++m) _Pragma("unroll") for (int k = 0; k < 2; ++k) dst[m][k] = *(const PG8_LAS bf16x8*)(lds + PG8_SA(b, h) + aoff + m * 2048 + k * 1024); } while (0)
; template <class Epi, class Sched, bool STAMP = false>
; __device__ __forceinline__ void gemm_phase(PG8_LAS unsigned char* lds, const Gemm g, const Sched& S, const Epi& E, unsigned long long* stamps) {
;     ...
;         for (int t = 0; t < nt; t += 2) {
;             const bool last = (t == nt - 2);
;             const char* a1 = cA + (size_t)(t + 1) * kstep;
;             const char* a2 = last ? nA : cA + (size_t)(t + 2) * kstep; const char* b2 = last ? nB : cB + (size_t)(t + 2) * kstep;
;             const char* a3 = a2 + kstep; const char* b3 = b2 + kstep;
;             if (last && has_next) S.a_ready(nxt);
;             PG8_LDB(B0, 0, 0); PG8_SCHED; PG8_LDA(At, 0, 0); PG8_STAGE(PG8_SA(1, 1), a1 + hstep, voffA);
;             PG8_WAIT_L(8); PG8_BAR; PG8_WAIT_L(0); PG8_MMA(0, 0, At, B0); PG8_BAR; PG8_SCHED;
;             PG8_LDB(B1, 0, 1); PG8_STAGE(PG8_SB(0, 0), b2, voffB);
;             PG8_BAR; PG8_WAIT_L(0); PG8_MMA(0, 1, At, B1); PG8_BAR;
;             PG8_LDA(At, 0, 1); PG8_STAGE(PG8_SA(0, 0), a2, voffA);
;             PG8_BAR; PG8_WAIT_L(0); PG8_MMA(1, 0, At, B0); PG8_BAR; PG8_SCHED;
;             PG8_STAGE(PG8_SB(0, 1), b2 + hstep, voffB);
;             PG8_WAIT_V(6); PG8_BAR; PG8_MMA(1, 1, At, B1); PG8_BAR;
;             PG8_LDB(B0, 1, 0); PG8_SCHED; PG8_LDA(At, 1, 0); PG8_STAGE(PG8_SA(0, 1), a2 + hstep, voffA);
;             PG8_WAIT_L(8); PG8_BAR; PG8_WAIT_L(0); PG8_MMA(0, 0, At, B0); PG8_BAR; PG8_SCHED;
;             PG8_LDB(B1, 1, 1); PG8_STAGE(PG8_SB(1, 0), b3, voffB);
;             PG8_BAR; PG8_WAIT_L(0); PG8_MMA(0, 1, At, B1); PG8_BAR;
;             PG8_LDA(At, 1, 1); PG8_STAGE(PG8_SA(1, 0), a3, voffA);
;             PG8_BAR; PG8_WAIT_L(0); PG8_MMA(1, 0, At, B0); PG8_BAR; PG8_SCHED;
;             PG8_STAGE(PG8_SB(1, 1), b3 + hstep, voffB);
;             PG8_WAIT_V(6); PG8_BAR; PG8_MMA(1, 1, At, B1); PG8_BAR;
;         }
.Lgu3_half_loop:
	ds_read_b128 v[140:143], v147
	ds_read_b128 v[170:173], v148
	ds_read_b128 v[174:177], v149
	ds_read_b128 v[178:181], v150
	s_add_u32 s36, s34, 0x100
	s_addc_u32 s37, s35, 0
	s_cmp_eq_u32 s10, 12
	s_cselect_b32 s43, s5, s37
	s_cselect_b32 s42, s4, s36
	s_cselect_b32 s41, s1, s78
	s_cselect_b32 s40, s0, s77
	s_mov_b32 m0, s67
	ds_read_b128 v[182:185], v145
	ds_read_b128 v[186:189], v145 offset:1024
	ds_read_b128 v[190:193], v145 offset:2048
	ds_read_b128 v[194:197], v145 offset:3072
	ds_read_b128 v[198:201], v145 offset:4096
	ds_read_b128 v[202:205], v145 offset:5120
	ds_read_b128 v[206:209], v145 offset:6144
	ds_read_b128 v[210:213], v145 offset:7168
	global_load_lds_dwordx4 v132, s[34:35]
	s_mov_b32 m0, s68
	s_nop 0
	global_load_lds_dwordx4 v134, s[34:35]
	s_waitcnt lgkmcnt(8)
	s_barrier
	s_waitcnt lgkmcnt(0)
	s_setprio 1
	s_waitcnt lgkmcnt(0)
	v_mfma_f32_16x16x32_bf16 v[124:127], v[140:143], v[182:185], v[124:127]
	v_mfma_f32_16x16x32_bf16 v[120:123], v[174:177], v[182:185], v[120:123]
	v_mfma_f32_16x16x32_bf16 v[108:111], v[140:143], v[190:193], v[108:111]
	v_mfma_f32_16x16x32_bf16 v[104:107], v[174:177], v[190:193], v[104:107]
	v_mfma_f32_16x16x32_bf16 v[92:95], v[140:143], v[198:201], v[92:95]
	v_mfma_f32_16x16x32_bf16 v[88:91], v[174:177], v[198:201], v[88:91]
	v_mfma_f32_16x16x32_bf16 v[76:79], v[140:143], v[206:209], v[76:79]
	v_mfma_f32_16x16x32_bf16 v[72:75], v[174:177], v[206:209], v[72:75]
	v_mfma_f32_16x16x32_bf16 v[124:127], v[170:173], v[186:189], v[124:127]
	v_mfma_f32_16x16x32_bf16 v[120:123], v[178:181], v[186:189], v[120:123]
	v_mfma_f32_16x16x32_bf16 v[108:111], v[170:173], v[194:197], v[108:111]
	v_mfma_f32_16x16x32_bf16 v[104:107], v[178:181], v[194:197], v[104:107]
	v_mfma_f32_16x16x32_bf16 v[92:95], v[170:173], v[202:205], v[92:95]
	v_mfma_f32_16x16x32_bf16 v[88:91], v[178:181], v[202:205], v[88:91]
	v_mfma_f32_16x16x32_bf16 v[76:79], v[170:173], v[210:213], v[76:79]
	v_mfma_f32_16x16x32_bf16 v[72:75], v[178:181], v[210:213], v[72:75]
	s_setprio 0
	s_barrier
	s_mov_b32 m0, s49
	s_nop 0
	global_load_lds_dwordx4 v130, s[40:41]
	s_mov_b32 m0, s52
	s_nop 0
	global_load_lds_dwordx4 v128, s[40:41]
	s_barrier
	s_waitcnt lgkmcnt(0)
	s_setprio 1
	s_waitcnt lgkmcnt(0)
	s_setprio 0
	s_mov_b32 m0, s46
	s_barrier
	ds_read_b128 v[182:185], v145 offset:16384
	ds_read_b128 v[186:189], v145 offset:17408
	ds_read_b128 v[190:193], v145 offset:18432
	ds_read_b128 v[194:197], v145 offset:19456
	ds_read_b128 v[198:201], v145 offset:20480
	ds_read_b128 v[202:205], v145 offset:21504
	ds_read_b128 v[206:209], v145 offset:22528
	ds_read_b128 v[210:213], v145 offset:23552
	global_load_lds_dwordx4 v130, s[42:43]
	s_mov_b32 m0, s53
	s_nop 0
	global_load_lds_dwordx4 v128, s[42:43]
	s_barrier
	s_waitcnt lgkmcnt(0)
	s_setprio 1
	s_waitcnt lgkmcnt(0)
	v_mfma_f32_16x16x32_bf16 v[60:63], v[140:143], v[182:185], v[60:63]
	v_mfma_f32_16x16x32_bf16 v[56:59], v[174:177], v[182:185], v[56:59]
	v_mfma_f32_16x16x32_bf16 v[44:47], v[140:143], v[190:193], v[44:47]
	v_mfma_f32_16x16x32_bf16 v[40:43], v[174:177], v[190:193], v[40:43]
	v_mfma_f32_16x16x32_bf16 v[28:31], v[140:143], v[198:201], v[28:31]
	v_mfma_f32_16x16x32_bf16 v[24:27], v[174:177], v[198:201], v[24:27]
	v_mfma_f32_16x16x32_bf16 v[12:15], v[140:143], v[206:209], v[12:15]
	v_mfma_f32_16x16x32_bf16 v[8:11], v[174:177], v[206:209], v[8:11]
	v_mfma_f32_16x16x32_bf16 v[60:63], v[170:173], v[186:189], v[60:63]
	v_mfma_f32_16x16x32_bf16 v[56:59], v[178:181], v[186:189], v[56:59]
	v_mfma_f32_16x16x32_bf16 v[44:47], v[170:173], v[194:197], v[44:47]
	v_mfma_f32_16x16x32_bf16 v[40:43], v[178:181], v[194:197], v[40:43]
	v_mfma_f32_16x16x32_bf16 v[28:31], v[170:173], v[202:205], v[28:31]
	v_mfma_f32_16x16x32_bf16 v[24:27], v[178:181], v[202:205], v[24:27]
	v_mfma_f32_16x16x32_bf16 v[12:15], v[170:173], v[210:213], v[12:15]
	v_mfma_f32_16x16x32_bf16 v[8:11], v[178:181], v[210:213], v[8:11]
	s_setprio 0
	s_barrier
	s_add_u32 s34, s40, 0x44000
	s_addc_u32 s35, s41, 0
	s_mov_b32 m0, s54
	s_nop 0
	s_mov_b32 m0, s55
	s_nop 0
	s_waitcnt vmcnt(4)
	s_barrier
	s_setprio 1
	s_setprio 0
	s_barrier
	ds_read_b128 v[140:143], v155
	ds_read_b128 v[170:173], v156
	ds_read_b128 v[174:177], v157
	ds_read_b128 v[178:181], v165
	s_add_u32 s34, s42, 0x44000
	s_addc_u32 s35, s43, 0
	s_mov_b32 m0, s56
	ds_read_b128 v[182:185], v145 offset:32768
	ds_read_b128 v[186:189], v145 offset:33792
	ds_read_b128 v[190:193], v145 offset:34816
	ds_read_b128 v[194:197], v145 offset:35840
	ds_read_b128 v[198:201], v145 offset:36864
	ds_read_b128 v[202:205], v145 offset:37888
	ds_read_b128 v[206:209], v145 offset:38912
	ds_read_b128 v[210:213], v145 offset:39936
	global_load_lds_dwordx4 v130, s[34:35]
	s_mov_b32 m0, s57
	s_nop 0
	global_load_lds_dwordx4 v128, s[34:35]
	s_waitcnt lgkmcnt(8)
	s_barrier
	s_waitcnt lgkmcnt(0)
	s_setprio 1
	s_waitcnt lgkmcnt(0)
	v_mfma_f32_16x16x32_bf16 v[124:127], v[140:143], v[182:185], v[124:127]
	v_mfma_f32_16x16x32_bf16 v[120:123], v[174:177], v[182:185], v[120:123]
	v_mfma_f32_16x16x32_bf16 v[108:111], v[140:143], v[190:193], v[108:111]
	v_mfma_f32_16x16x32_bf16 v[104:107], v[174:177], v[190:193], v[104:107]
	v_mfma_f32_16x16x32_bf16 v[92:95], v[140:143], v[198:201], v[92:95]
	v_mfma_f32_16x16x32_bf16 v[88:91], v[174:177], v[198:201], v[88:91]
	v_mfma_f32_16x16x32_bf16 v[76:79], v[140:143], v[206:209], v[76:79]
	v_mfma_f32_16x16x32_bf16 v[72:75], v[174:177], v[206:209], v[72:75]
	v_mfma_f32_16x16x32_bf16 v[124:127], v[170:173], v[186:189], v[124:127]
	v_mfma_f32_16x16x32_bf16 v[120:123], v[178:181], v[186:189], v[120:123]
	v_mfma_f32_16x16x32_bf16 v[108:111], v[170:173], v[194:197], v[108:111]
	v_mfma_f32_16x16x32_bf16 v[104:107], v[178:181], v[194:197], v[104:107]
	v_mfma_f32_16x16x32_bf16 v[92:95], v[170:173], v[202:205], v[92:95]
	v_mfma_f32_16x16x32_bf16 v[88:91], v[178:181], v[202:205], v[88:91]
	v_mfma_f32_16x16x32_bf16 v[76:79], v[170:173], v[210:213], v[76:79]
	v_mfma_f32_16x16x32_bf16 v[72:75], v[178:181], v[210:213], v[72:75]
	s_setprio 0
	s_barrier
; #define PG8_STAGE(bufoff, gbase, voff) do { _Pragma("unroll") for (int _i = 0; _i < 2; ++_i) \
;         __builtin_amdgcn_global_load_lds((const unsigned*)((const char*)(gbase) + (voff)[_i]), (PG8_LAS unsigned*)(lds + (bufoff) + ldsw + _i * 8192), 16, 0, 0); } while (0)
; #define PG8_LDA(dst, b, h) do { _Pragma("unroll") for (int m = 0; m < 4; ++m) _Pragma("unroll") for (int k = 0; k < 2; ++k) dst[m][k] = *(const PG8_LAS bf16x8*)(lds + PG8_SA(b, h) + aoff + m * 2048 + k * 1024); } while (0)
; #define PG8_LDB(dst, b, h) do { _Pragma("unroll") for (int n = 0; n < 2; ++n) _Pragma("unroll") for (int k = 0; k < 2; ++k) dst[n][k] = *(const PG8_LAS bf16x8*)(lds + PG8_SB(b, h) + boff + n * 2048 + k * 1024); } while (0)
; #define PG8_MMA(ai, bj, At, Bt) do { __builtin_amdgcn_s_setprio(1); _Pragma("unroll") for (int m = 0; m < 4; ++m) _Pragma("unroll") for (int n = 0; n < 2; ++n) _Pragma("unroll") for (int k = 0; k < 2; ++k) \
;         acc[ai][bj][m][n] = __builtin_amdgcn_mfma_f32_16x16x32_bf16(Bt[n][k], At[m][k], acc[ai][bj][m][n], 0, 0, 0); __builtin_amdgcn_s_setprio(0); } while (0)
; #define PG8_WAIT_V(n) asm volatile("s_waitcnt vmcnt(" #n ")" ::: "memory")
; #define PG8_WAIT_L(n) asm volatile("s_waitcnt lgkmcnt(" #n ")" ::: "memory")
; #define PG8_BAR __builtin_amdgcn_s_barrier()
; #define PG8_SCHED __builtin_amdgcn_sched_barrier(0)
; template <class Epi, class Sched, bool STAMP = false>
; __device__ __forceinline__ void gemm_phase(PG8_LAS unsigned char* lds, const Gemm g, const Sched& S, const Epi& E, unsigned long long* stamps) {
;     ...
;             PG8_LDB(B0, 1, 0); PG8_SCHED; PG8_LDA(At, 1, 0); PG8_STAGE(PG8_SA(0, 1), a2 + hstep, voffA);
;             PG8_WAIT_L(8); PG8_BAR; PG8_WAIT_L(0); PG8_MMA(0, 0, At, B0); PG8_BAR; PG8_SCHED;
;             PG8_LDB(B1, 1, 1); PG8_STAGE(PG8_SB(1, 0), b3, voffB);
;             PG8_BAR; PG8_WAIT_L(0); PG8_MMA(0, 1, At, B1); PG8_BAR;
;             PG8_LDA(At, 1, 1); PG8_STAGE(PG8_SA(1, 0), a3, voffA);
;             PG8_BAR; PG8_WAIT_L(0); PG8_MMA(1, 0, At, B0); PG8_BAR; PG8_SCHED;
;             PG8_STAGE(PG8_SB(1, 1), b3 + hstep, voffB);
;             PG8_WAIT_V(6); PG8_BAR; PG8_MMA(1, 1, At, B1); PG8_BAR;
;         }
	s_mov_b32 m0, s60
	s_add_u32 s100, s40, 0x80
	s_addc_u32 s101, s41, 0
	global_load_lds_dwordx4 v130, s[100:101]
	s_mov_b32 m0, s61
	s_nop 0
	global_load_lds_dwordx4 v128, s[100:101]
	s_barrier
	s_waitcnt lgkmcnt(0)
	s_setprio 1
	s_waitcnt lgkmcnt(0)
	s_setprio 0
	s_mov_b32 m0, s62
	s_barrier
	ds_read_b128 v[182:185], v145 offset:49152
	ds_read_b128 v[186:189], v145 offset:50176
	ds_read_b128 v[190:193], v145 offset:51200
	ds_read_b128 v[194:197], v145 offset:52224
	ds_read_b128 v[198:201], v145 offset:53248
	ds_read_b128 v[202:205], v145 offset:54272
	ds_read_b128 v[206:209], v145 offset:55296
	ds_read_b128 v[210:213], v145 offset:56320
	s_add_u32 s100, s42, 0x80
	s_addc_u32 s101, s43, 0
	global_load_lds_dwordx4 v130, s[100:101]
	s_mov_b32 m0, s63
	s_nop 0
	global_load_lds_dwordx4 v128, s[100:101]
	s_barrier
	s_waitcnt lgkmcnt(0)
	s_setprio 1
	s_waitcnt lgkmcnt(0)
	v_mfma_f32_16x16x32_bf16 v[60:63], v[140:143], v[182:185], v[60:63]
	v_mfma_f32_16x16x32_bf16 v[56:59], v[174:177], v[182:185], v[56:59]
	v_mfma_f32_16x16x32_bf16 v[44:47], v[140:143], v[190:193], v[44:47]
	v_mfma_f32_16x16x32_bf16 v[40:43], v[174:177], v[190:193], v[40:43]
	v_mfma_f32_16x16x32_bf16 v[28:31], v[140:143], v[198:201], v[28:31]
	v_mfma_f32_16x16x32_bf16 v[24:27], v[174:177], v[198:201], v[24:27]
	v_mfma_f32_16x16x32_bf16 v[12:15], v[140:143], v[206:209], v[12:15]
	v_mfma_f32_16x16x32_bf16 v[8:11], v[174:177], v[206:209], v[8:11]
	v_mfma_f32_16x16x32_bf16 v[60:63], v[170:173], v[186:189], v[60:63]
	v_mfma_f32_16x16x32_bf16 v[56:59], v[178:181], v[186:189], v[56:59]
	v_mfma_f32_16x16x32_bf16 v[44:47], v[170:173], v[194:197], v[44:47]
	v_mfma_f32_16x16x32_bf16 v[40:43], v[178:181], v[194:197], v[40:43]
	v_mfma_f32_16x16x32_bf16 v[28:31], v[170:173], v[202:205], v[28:31]
	v_mfma_f32_16x16x32_bf16 v[24:27], v[178:181], v[202:205], v[24:27]
	v_mfma_f32_16x16x32_bf16 v[12:15], v[170:173], v[210:213], v[12:15]
	v_mfma_f32_16x16x32_bf16 v[8:11], v[178:181], v[210:213], v[8:11]
	s_setprio 0
	s_barrier
	s_add_u32 s34, s40, 0x44080
	s_addc_u32 s35, s41, 0
	s_mov_b32 m0, s64
	s_nop 0
	s_mov_b32 m0, s65
	s_nop 0
	s_waitcnt vmcnt(4)
	s_barrier
	s_setprio 1
	s_setprio 0
	s_add_i32 s10, s10, 2
	s_add_u32 s77, s77, 0x100
	s_addc_u32 s78, s78, 0
	s_cmp_gt_u32 s10, 13
	s_mov_b64 s[34:35], s[36:37]
	s_barrier
	s_cbranch_scc0 .Lgu3_half_loop
; DI float ex2(float x) { return __builtin_amdgcn_exp2f(x); }
;     DI void operator()(const f32x4 (&acc)[2][2][4][2], const Unit& u, int wr, int wc, int fr, int fq) const {
;         const int row0 = u.pm * BM + wr * 64 + fr, hcol0 = ((u.pn * BM + wc * 32) >> 1) + 4 * fq;
; #pragma unroll
;         for (int ai = 0; ai < 2; ++ai)
; #pragma unroll
;             for (int m = 0; m < 4; ++m) { u16* rowp = O + (size_t)(row0 + ai * HALF + m * 16) * ldc + hcol0;
; #pragma unroll
;                 for (int bj = 0; bj < 2; ++bj) { const f32x4 g = acc[ai][bj][m][0], up = acc[ai][bj][m][1]; float r[4];
; #pragma unroll
;                     for (int j = 0; j < 4; ++j) r[j] = g[j] * up[j] * __builtin_amdgcn_rcpf(1.f + ex2(-LOG2E * g[j]));
;                     uint2 w = {pack2(r[0], r[1]), pack2(r[2], r[3])}; *(uint2*)(rowp + bj * (HALF / 2)) = w; } }
;     }
	v_exp_f32_e64 v171, -v124
	v_exp_f32_e64 v175, -v125
	s_lshl_b32 s10, s76, 8
	v_add_f32_e32 v171, 1.0, v171
	v_rcp_f32_e32 v174, v171
	v_add_f32_e32 v171, 1.0, v175
	v_exp_f32_e64 v176, -v126
	v_exp_f32_e64 v177, -v127
	v_rcp_f32_e32 v175, v171
	v_add_f32_e32 v171, 1.0, v176
	v_rcp_f32_e32 v176, v171
	v_add_f32_e32 v171, 1.0, v177
	v_rcp_f32_e32 v177, v171
	v_pk_mul_f32 v[122:123], v[126:127], v[122:123]
	v_pk_mul_f32 v[120:121], v[124:125], v[120:121]
	s_or_b32 s10, s10, s59
	s_or_b32 s10, s10, s98
	v_pk_mul_f32 v[120:121], v[120:121], v[174:175]
	v_pk_mul_f32 v[122:123], v[122:123], v[176:177]
	s_ashr_i32 s10, s10, 1
	v_cvt_pk_bf16_f32 v120, v120, v121
	v_cvt_pk_bf16_f32 v121, v122, v123
	v_or_b32_e32 v140, s10, v146
	v_lshl_add_u32 v170, s75, 8, v144
	v_ashrrev_i32_e32 v141, 31, v140
	v_mov_b64_e32 v[142:143], s[12:13]
	v_mad_i64_i32 v[172:173], s[34:35], v170, s69, v[142:143]
	v_lshlrev_b64 v[140:141], 1, v[140:141]
	v_lshl_add_u64 v[172:173], v[172:173], 0, v[140:141]
	global_store_dwordx2 v[172:173], v[120:121], off
	v_exp_f32_e64 v114, -v108
	v_exp_f32_e64 v115, -v109
	v_exp_f32_e64 v116, -v110
	v_exp_f32_e64 v117, -v111
	v_add_f32_e32 v114, 1.0, v114
	v_add_f32_e32 v115, 1.0, v115
	v_add_f32_e32 v116, 1.0, v116
	v_add_f32_e32 v117, 1.0, v117
	v_rcp_f32_e32 v114, v114
	v_rcp_f32_e32 v115, v115
	v_rcp_f32_e32 v116, v116
	v_rcp_f32_e32 v117, v117
	v_pk_mul_f32 v[106:107], v[110:111], v[106:107]
	v_pk_mul_f32 v[104:105], v[108:109], v[104:105]
	v_pk_mul_f32 v[104:105], v[104:105], v[114:115]
	v_pk_mul_f32 v[106:107], v[106:107], v[116:117]
	v_cvt_pk_bf16_f32 v104, v104, v105
	v_cvt_pk_bf16_f32 v105, v106, v107
	v_or_b32_e32 v112, 16, v170
	v_mad_i64_i32 v[112:113], s[34:35], v112, s69, v[142:143]
	v_lshl_add_u64 v[112:113], v[112:113], 0, v[140:141]
	global_store_dwordx2 v[112:113], v[104:105], off
	v_exp_f32_e64 v98, -v92
	v_exp_f32_e64 v99, -v93
	v_exp_f32_e64 v100, -v94
	v_exp_f32_e64 v101, -v95
	v_add_f32_e32 v98, 1.0, v98
	v_add_f32_e32 v99, 1.0, v99
	v_add_f32_e32 v100, 1.0, v100
	v_add_f32_e32 v101, 1.0, v101
	v_rcp_f32_e32 v98, v98
	v_rcp_f32_e32 v99, v99
	v_rcp_f32_e32 v100, v100
	v_rcp_f32_e32 v101, v101
	v_pk_mul_f32 v[90:91], v[94:95], v[90:91]
	v_pk_mul_f32 v[88:89], v[92:93], v[88:89]
	v_pk_mul_f32 v[88:89], v[88:89], v[98:99]
	v_pk_mul_f32 v[90:91], v[90:91], v[100:101]
	v_cvt_pk_bf16_f32 v88, v88, v89
	v_cvt_pk_bf16_f32 v89, v90, v91
	v_or_b32_e32 v96, 32, v170
	v_mad_i64_i32 v[96:97], s[34:35], v96, s69, v[142:143]
	v_lshl_add_u64 v[96:97], v[96:97], 0, v[140:141]
	global_store_dwordx2 v[96:97], v[88:89], off
	v_exp_f32_e64 v82, -v76
	v_exp_f32_e64 v83, -v77
	v_exp_f32_e64 v84, -v78
	v_exp_f32_e64 v85, -v79
	v_add_f32_e32 v82, 1.0, v82
	v_add_f32_e32 v83, 1.0, v83
	v_add_f32_e32 v84, 1.0, v84
	v_add_f32_e32 v85, 1.0, v85
	v_rcp_f32_e32 v82, v82
	v_rcp_f32_e32 v83, v83
	v_rcp_f32_e32 v84, v84
	v_rcp_f32_e32 v85, v85
	v_pk_mul_f32 v[74:75], v[78:79], v[74:75]
	v_pk_mul_f32 v[72:73], v[76:77], v[72:73]
	v_pk_mul_f32 v[72:73], v[72:73], v[82:83]
	v_pk_mul_f32 v[74:75], v[74:75], v[84:85]
	v_cvt_pk_bf16_f32 v72, v72, v73
	v_cvt_pk_bf16_f32 v73, v74, v75
	v_or_b32_e32 v80, 48, v170
	v_mad_i64_i32 v[80:81], s[34:35], v80, s69, v[142:143]
	v_lshl_add_u64 v[80:81], v[80:81], 0, v[140:141]
	global_store_dwordx2 v[80:81], v[72:73], off
	v_exp_f32_e64 v66, -v60
	v_exp_f32_e64 v67, -v61
	v_exp_f32_e64 v68, -v62
	v_exp_f32_e64 v69, -v63
	v_add_f32_e32 v66, 1.0, v66
	v_add_f32_e32 v67, 1.0, v67
	v_add_f32_e32 v68, 1.0, v68
	v_add_f32_e32 v69, 1.0, v69
	v_rcp_f32_e32 v66, v66
	v_rcp_f32_e32 v67, v67
	v_rcp_f32_e32 v68, v68
	v_rcp_f32_e32 v69, v69
	v_pk_mul_f32 v[58:59], v[62:63], v[58:59]
	v_pk_mul_f32 v[56:57], v[60:61], v[56:57]
	v_pk_mul_f32 v[56:57], v[56:57], v[66:67]
	v_pk_mul_f32 v[58:59], v[58:59], v[68:69]
	v_cvt_pk_bf16_f32 v56, v56, v57
	v_cvt_pk_bf16_f32 v57, v58, v59
	v_add_u32_e32 v64, 0x80, v170
	v_mad_i64_i32 v[64:65], s[34:35], v64, s69, v[142:143]
	v_lshl_add_u64 v[64:65], v[64:65], 0, v[140:141]
	global_store_dwordx2 v[64:65], v[56:57], off
	v_exp_f32_e64 v50, -v44
	v_exp_f32_e64 v51, -v45
	v_exp_f32_e64 v52, -v46
	v_exp_f32_e64 v53, -v47
	v_add_f32_e32 v50, 1.0, v50
	v_add_f32_e32 v51, 1.0, v51
	v_add_f32_e32 v52, 1.0, v52
	v_add_f32_e32 v53, 1.0, v53
	v_rcp_f32_e32 v50, v50
	v_rcp_f32_e32 v51, v51
	v_rcp_f32_e32 v52, v52
	v_rcp_f32_e32 v53, v53
	v_pk_mul_f32 v[42:43], v[46:47], v[42:43]
	v_pk_mul_f32 v[40:41], v[44:45], v[40:41]
	v_pk_mul_f32 v[40:41], v[40:41], v[50:51]
	v_pk_mul_f32 v[42:43], v[42:43], v[52:53]
	v_cvt_pk_bf16_f32 v40, v40, v41
	v_cvt_pk_bf16_f32 v41, v42, v43
	v_add_u32_e32 v48, 0x90, v170
	v_mad_i64_i32 v[48:49], s[34:35], v48, s69, v[142:143]
	v_lshl_add_u64 v[48:49], v[48:49], 0, v[140:141]
	global_store_dwordx2 v[48:49], v[40:41], off
	v_exp_f32_e64 v34, -v28
	v_exp_f32_e64 v35, -v29
	v_exp_f32_e64 v36, -v30
	v_exp_f32_e64 v37, -v31
	v_add_f32_e32 v34, 1.0, v34
	v_add_f32_e32 v35, 1.0, v35
	v_add_f32_e32 v36, 1.0, v36
	v_add_f32_e32 v37, 1.0, v37
	v_rcp_f32_e32 v34, v34
	v_rcp_f32_e32 v35, v35
	v_rcp_f32_e32 v36, v36
	v_rcp_f32_e32 v37, v37
	v_pk_mul_f32 v[26:27], v[30:31], v[26:27]
	v_pk_mul_f32 v[24:25], v[28:29], v[24:25]
	v_pk_mul_f32 v[24:25], v[24:25], v[34:35]
	v_pk_mul_f32 v[26:27], v[26:27], v[36:37]
	v_cvt_pk_bf16_f32 v24, v24, v25
	v_cvt_pk_bf16_f32 v25, v26, v27
	v_add_u32_e32 v32, 0xa0, v170
	v_mad_i64_i32 v[32:33], s[34:35], v32, s69, v[142:143]
	v_lshl_add_u64 v[32:33], v[32:33], 0, v[140:141]
	global_store_dwordx2 v[32:33], v[24:25], off
	v_exp_f32_e64 v18, -v12
	v_exp_f32_e64 v19, -v13
	v_exp_f32_e64 v20, -v14
	v_exp_f32_e64 v21, -v15
	v_add_f32_e32 v18, 1.0, v18
	v_add_f32_e32 v19, 1.0, v19
	v_add_f32_e32 v20, 1.0, v20
	v_add_f32_e32 v21, 1.0, v21
	v_rcp_f32_e32 v18, v18
	v_rcp_f32_e32 v19, v19
	v_rcp_f32_e32 v20, v20
	v_rcp_f32_e32 v21, v21
	v_pk_mul_f32 v[10:11], v[14:15], v[10:11]
	v_pk_mul_f32 v[8:9], v[12:13], v[8:9]
	v_pk_mul_f32 v[8:9], v[8:9], v[18:19]
	v_pk_mul_f32 v[10:11], v[10:11], v[20:21]
	v_cvt_pk_bf16_f32 v8, v8, v9
	v_cvt_pk_bf16_f32 v9, v10, v11
	v_add_u32_e32 v16, 0xb0, v170
	v_mad_i64_i32 v[16:17], s[34:35], v16, s69, v[142:143]
	v_lshl_add_u64 v[16:17], v[16:17], 0, v[140:141]
	global_store_dwordx2 v[16:17], v[8:9], off
	s_and_b64 vcc, exec, s[2:3]
	s_mov_b32 s76, s70
	s_mov_b32 s75, s71
	s_mov_b64 s[36:37], s[0:1]
	s_mov_b64 s[34:35], s[4:5]

; DI int ltid() { int t = threadIdx.x; asm volatile("" : "+v"(t)); return t; }
; DI int lbid() { int b = blockIdx.x; asm volatile("" : "+s"(b)); return b; }
; DI void combine_phase(const Params& p, int layer) {
;     ...
;   const int total = S * 48;
;   for (int idx = lbid() * NTHR + ltid(); idx < total; idx += gridDim.x * NTHR) {
;     const int tok = idx / 48, ch = idx - tok * 48, head = ch >> 3;
;     float acc[8] = {0, 0, 0, 0, 0, 0, 0, 0};
;     float lsum = 0.f;
; #pragma unroll
;     for (int b = 0; b < 3; ++b) {
;       const uint4 v = *(const uint4*)(part + (size_t)b * S * 384 + (size_t)tok * 384 + ch * 8);
;       lsum += lpart[(size_t)b * S * 8 + (size_t)tok * 8 + head];
.LBB0_651:
	s_or_b64 exec, exec, s[0:1]
	s_mov_b32 s2, s92
	v_mov_b32_e32 v1, v158
	s_barrier
	s_mov_b32 s0, 0xc0000
	v_lshl_add_u32 v0, s2, 9, v1
	v_cmp_gt_i32_e32 vcc, s0, v0
	s_and_saveexec_b64 s[0:1], vcc
	s_cbranch_execz .LBB0_654
	v_lshlrev_b32_e32 v1, 3, v1
	s_lshl_b32 s4, s11, 9
	v_lshl_add_u32 v2, s2, 12, v1
	s_lshl_b32 s5, s11, 12
	s_mov_b64 s[2:3], 0
	s_mov_b32 s6, 0x2aaaaaab
	s_movk_i32 s7, 0xffd0
	s_movk_i32 s10, 0x300
	v_mov_b64_e32 v[4:5], s[14:15]
	s_movk_i32 s18, 0xfe80
	s_mov_b32 s19, 0xc00000
	s_mov_b32 s34, 0x80000
	s_mov_b32 s35, 0x1800000
	s_mov_b32 s36, 0x100000
	s_movk_i32 s37, 0x880
	v_mov_b64_e32 v[6:7], s[26:27]
	s_mov_b32 s40, 0xbffff
	v_mov_b32_e32 v100, v0
	v_mov_b32_e32 v102, v2
	v_mul_hi_i32 v101, v100, s6
	v_lshrrev_b32_e32 v103, 31, v101
	v_ashrrev_i32_e32 v101, 3, v101
	v_add_u32_e32 v120, v101, v103
	v_mad_u64_u32 v[112:113], s[42:43], v120, s18, v[102:103]
	v_ashrrev_i32_e32 v113, 31, v112
	v_mad_i64_i32 v[110:111], s[42:43], v120, s10, v[4:5]
	v_lshlrev_b64 v[122:123], 1, v[112:113]
	v_mad_u64_u32 v[108:109], s[42:43], v120, s7, v[100:101]
	v_lshl_add_u64 v[112:113], v[110:111], 0, v[122:123]
	v_ashrrev_i32_e32 v108, 3, v108
	v_add_co_u32_e32 v126, vcc, s19, v112
	v_ashrrev_i32_e32 v121, 31, v120
	v_ashrrev_i32_e32 v109, 31, v108
	s_nop 1
	v_addc_co_u32_e32 v127, vcc, 0, v113, vcc
	v_lshlrev_b64 v[114:115], 5, v[120:121]
	v_lshl_add_u64 v[116:117], v[108:109], 2, s[28:29]
	v_add_co_u32_e32 v128, vcc, s35, v112
	v_lshl_add_u64 v[124:125], v[116:117], 0, v[114:115]
	s_nop 1
	v_addc_co_u32_e32 v129, vcc, 0, v113, vcc
	global_load_dwordx4 v[108:111], v[112:113], off
	global_load_dword v101, v[124:125], off
	global_load_dwordx4 v[112:115], v[126:127], off
	global_load_dwordx4 v[116:119], v[128:129], off
	v_add_co_u32_e32 v126, vcc, s34, v124
	s_nop 1
	v_addc_co_u32_e32 v127, vcc, 0, v125, vcc
	v_add_co_u32_e32 v124, vcc, s36, v124
	s_nop 1
	v_addc_co_u32_e32 v125, vcc, 0, v125, vcc
	global_load_dword v103, v[126:127], off
	global_load_dword v134, v[124:125], off
	s_waitcnt vmcnt(0)
	s_branch .Lpl3_aw

; DI float bflo(unsigned u) { return __uint_as_float(u << 16); }
; DI float bfhi(unsigned u) { return __uint_as_float(u & 0xffff0000u); }
; DI int ltid() { int t = threadIdx.x; asm volatile("" : "+v"(t)); return t; }
; DI int lbid() { int b = blockIdx.x; asm volatile("" : "+s"(b)); return b; }
; DI void combine_phase(const Params& p, int layer) {
;     ...
;   for (int idx = lbid() * NTHR + ltid(); idx < total; idx += gridDim.x * NTHR) {
;     const int tok = idx / 48, ch = idx - tok * 48, head = ch >> 3;
;     float acc[8] = {0, 0, 0, 0, 0, 0, 0, 0};
;     float lsum = 0.f;
; #pragma unroll
;     for (int b = 0; b < 3; ++b) {
;       const uint4 v = *(const uint4*)(part + (size_t)b * S * 384 + (size_t)tok * 384 + ch * 8);
;       lsum += lpart[(size_t)b * S * 8 + (size_t)tok * 8 + head];
;       acc[0] += bflo(v.x); acc[1] += bfhi(v.x);
;       acc[2] += bflo(v.y); acc[3] += bfhi(v.y);
;       acc[4] += bflo(v.z); acc[5] += bfhi(v.z);
;       acc[6] += bflo(v.w); acc[7] += bfhi(v.w);
;     }
;     const float inv = 1.f / lsum;
;     uint4 o = {pack2(acc[0] * inv, acc[1] * inv), pack2(acc[2] * inv, acc[3] * inv), pack2(acc[4] * inv, acc[5] * inv),
;                pack2(acc[6] * inv, acc[7] * inv)};
;     *(uint4*)(mixed + (size_t)tok * LDH + ch * 8) = o;
;   }
.Lpl3_aw:
	v_mul_hi_i32 v1, v0, s6
	v_lshrrev_b32_e32 v3, 31, v1
	v_ashrrev_i32_e32 v1, 3, v1
	v_add_u32_e32 v20, v1, v3
	v_mad_u64_u32 v[12:13], s[42:43], v20, s18, v[2:3]
	v_ashrrev_i32_e32 v13, 31, v12
	v_mad_i64_i32 v[10:11], s[42:43], v20, s10, v[4:5]
	v_lshlrev_b64 v[22:23], 1, v[12:13]
	v_mad_u64_u32 v[8:9], s[42:43], v20, s7, v[0:1]
	v_lshl_add_u64 v[12:13], v[10:11], 0, v[22:23]
	v_ashrrev_i32_e32 v8, 3, v8
	v_add_co_u32_e32 v26, vcc, s19, v12
	v_ashrrev_i32_e32 v21, 31, v20
	v_ashrrev_i32_e32 v9, 31, v8
	v_addc_co_u32_e32 v27, vcc, 0, v13, vcc
	v_lshlrev_b64 v[14:15], 5, v[20:21]
	v_lshl_add_u64 v[16:17], v[8:9], 2, s[28:29]
	v_add_co_u32_e32 v28, vcc, s35, v12
	v_lshl_add_u64 v[24:25], v[16:17], 0, v[14:15]
	s_nop 0
	v_addc_co_u32_e32 v29, vcc, 0, v13, vcc
	v_mov_b64_e32 v[8:9], v[108:109]
	v_mov_b64_e32 v[10:11], v[110:111]
	v_mov_b32_e32 v1, v101
	s_nop 0
	v_mov_b64_e32 v[12:13], v[112:113]
	v_mov_b64_e32 v[14:15], v[114:115]
	v_mov_b64_e32 v[16:17], v[116:117]
	v_mov_b64_e32 v[18:19], v[118:119]
	v_add_co_u32_e32 v26, vcc, s34, v24
	v_mad_i64_i32 v[20:21], s[42:43], v20, s37, v[6:7]
	s_nop 0
	v_addc_co_u32_e32 v27, vcc, 0, v25, vcc
	v_add_co_u32_e32 v24, vcc, s36, v24
	v_lshl_add_u64 v[20:21], v[20:21], 0, v[22:23]
	s_nop 0
	v_addc_co_u32_e32 v25, vcc, 0, v25, vcc
	v_mov_b32_e32 v3, v103
	v_mov_b32_e32 v34, v134
	v_add_u32_e32 v0, s4, v0
	v_cmp_lt_i32_e32 vcc, s40, v0
	s_or_b64 s[2:3], vcc, s[2:3]
	v_add_u32_e32 v2, s5, v2
	s_mov_b64 s[98:99], exec
	s_andn2_b64 exec, exec, s[2:3]
	s_cbranch_execz .Lpl3_np
	v_mov_b32_e32 v100, v0
	v_mov_b32_e32 v102, v2
	v_mul_hi_i32 v101, v100, s6
	v_lshrrev_b32_e32 v103, 31, v101
	v_ashrrev_i32_e32 v101, 3, v101
	v_add_u32_e32 v120, v101, v103
	v_mad_u64_u32 v[112:113], s[42:43], v120, s18, v[102:103]
	v_ashrrev_i32_e32 v113, 31, v112
	v_mad_i64_i32 v[110:111], s[42:43], v120, s10, v[4:5]
	v_lshlrev_b64 v[122:123], 1, v[112:113]
	v_mad_u64_u32 v[108:109], s[42:43], v120, s7, v[100:101]
	v_lshl_add_u64 v[112:113], v[110:111], 0, v[122:123]
	v_ashrrev_i32_e32 v108, 3, v108
	v_add_co_u32_e32 v126, vcc, s19, v112
	v_ashrrev_i32_e32 v121, 31, v120
	v_ashrrev_i32_e32 v109, 31, v108
	s_nop 1
	v_addc_co_u32_e32 v127, vcc, 0, v113, vcc
	v_lshlrev_b64 v[114:115], 5, v[120:121]
	v_lshl_add_u64 v[116:117], v[108:109], 2, s[28:29]
	v_add_co_u32_e32 v128, vcc, s35, v112
	v_lshl_add_u64 v[124:125], v[116:117], 0, v[114:115]
	s_nop 1
	v_addc_co_u32_e32 v129, vcc, 0, v113, vcc
	global_load_dwordx4 v[108:111], v[112:113], off
	global_load_dword v101, v[124:125], off
	global_load_dwordx4 v[112:115], v[126:127], off
	global_load_dwordx4 v[116:119], v[128:129], off
	v_add_co_u32_e32 v126, vcc, s34, v124
	s_nop 1
	v_addc_co_u32_e32 v127, vcc, 0, v125, vcc
	v_add_co_u32_e32 v124, vcc, s36, v124
	s_nop 1
	v_addc_co_u32_e32 v125, vcc, 0, v125, vcc
	global_load_dword v103, v[126:127], off
	global_load_dword v134, v[124:125], off
.Lpl3_np:
	s_mov_b64 exec, s[98:99]
	v_add_f32_e32 v1, 0, v1
	v_lshlrev_b32_e32 v22, 16, v8
	v_and_b32_e32 v23, 0xffff0000, v8
	v_lshlrev_b32_e32 v8, 16, v9
	v_and_b32_e32 v9, 0xffff0000, v9
	v_lshlrev_b32_e32 v26, 16, v12
	v_and_b32_e32 v27, 0xffff0000, v12
	v_lshlrev_b32_e32 v12, 16, v13
	v_and_b32_e32 v13, 0xffff0000, v13
	v_pk_add_f32 v[8:9], v[8:9], 0 op_sel_hi:[1,0]
	v_lshlrev_b32_e32 v30, 16, v16
	v_and_b32_e32 v31, 0xffff0000, v16
	v_lshlrev_b32_e32 v16, 16, v17
	v_add_f32_e32 v1, v1, v3
	v_add_f32_e32 v1, v1, v34
	v_and_b32_e32 v17, 0xffff0000, v17
	v_pk_add_f32 v[8:9], v[8:9], v[12:13]
	v_div_scale_f32 v3, s[42:43], v1, v1, 1.0
	v_pk_add_f32 v[8:9], v[8:9], v[16:17]
	v_rcp_f32_e32 v17, v3
	v_lshlrev_b32_e32 v24, 16, v10
	v_and_b32_e32 v25, 0xffff0000, v10
	v_lshlrev_b32_e32 v10, 16, v11
	v_and_b32_e32 v11, 0xffff0000, v11
	v_lshlrev_b32_e32 v28, 16, v14
	v_and_b32_e32 v29, 0xffff0000, v14
	v_lshlrev_b32_e32 v14, 16, v15
	v_and_b32_e32 v15, 0xffff0000, v15
	v_pk_add_f32 v[10:11], v[10:11], 0 op_sel_hi:[1,0]
	v_lshlrev_b32_e32 v32, 16, v18
	v_and_b32_e32 v33, 0xffff0000, v18
	v_lshlrev_b32_e32 v18, 16, v19
	v_and_b32_e32 v19, 0xffff0000, v19
	v_pk_add_f32 v[10:11], v[10:11], v[14:15]
	v_div_scale_f32 v16, vcc, 1.0, v1, 1.0
	v_pk_add_f32 v[10:11], v[10:11], v[18:19]
	v_fma_f32 v18, -v3, v17, 1.0
	v_fmac_f32_e32 v17, v18, v17
	v_mul_f32_e32 v18, v16, v17
	v_fma_f32 v19, -v3, v18, v16
	v_fmac_f32_e32 v18, v19, v17
	v_pk_add_f32 v[22:23], v[22:23], 0 op_sel_hi:[1,0]
	v_pk_add_f32 v[24:25], v[24:25], 0 op_sel_hi:[1,0]
	v_fma_f32 v3, -v3, v18, v16
	v_pk_add_f32 v[22:23], v[22:23], v[26:27]
	v_pk_add_f32 v[12:13], v[24:25], v[28:29]
	v_div_fmas_f32 v3, v3, v17, v18
	v_pk_add_f32 v[14:15], v[22:23], v[30:31]
	v_pk_add_f32 v[12:13], v[12:13], v[32:33]
	v_div_fixup_f32 v16, v3, v1, 1.0
	v_pk_mul_f32 v[14:15], v[14:15], v[16:17] op_sel_hi:[1,0]
	v_pk_mul_f32 v[18:19], v[8:9], v[16:17] op_sel_hi:[1,0]
	v_pk_mul_f32 v[12:13], v[12:13], v[16:17] op_sel_hi:[1,0]
	v_pk_mul_f32 v[16:17], v[16:17], v[10:11] op_sel_hi:[0,1]
	v_cvt_pk_bf16_f32 v8, v14, v15
	v_cvt_pk_bf16_f32 v9, v18, v19
	v_cvt_pk_bf16_f32 v10, v12, v13
	v_cvt_pk_bf16_f32 v11, v16, v17
	global_store_dwordx4 v[20:21], v[8:11], off
	s_andn2_b64 exec, exec, s[2:3]
	s_cbranch_execnz .Lpl3_top

; DI float bflo(unsigned u) { return __uint_as_float(u << 16); }
; DI float bfhi(unsigned u) { return __uint_as_float(u & 0xffff0000u); }
; DI int ltid() { int t = threadIdx.x; asm volatile("" : "+v"(t)); return t; }
; DI int lbid() { int b = blockIdx.x; asm volatile("" : "+s"(b)); return b; }
; DI void combine_phase(const Params& p, int layer) {
;     ...
;     const int tid = ltid(), lane = tid & 63, wid = tid >> 6;
;     const float* dl = p.dlam + layer * 128;
;     float a = 0.f, b = 0.f;
;     if (lane < 32) { a = dl[lane] * dl[32 + lane]; b = dl[64 + lane] * dl[96 + lane]; }
;     a = wave_sum(a);
;     b = wave_sum(b);
;     const float lam_init = 0.8f - 0.6f * expf(-0.3f * (float)layer);
;     const float lam = expf(a) - expf(b) + lam_init;
;     const int hs = lane >> 5, dq = lane & 31;
;     const int nch = hs ? NCH3 : NCH2;
;     const float g0 = p.subln[layer * 64 + 2 * dq], g1 = p.subln[layer * 64 + 2 * dq + 1];
;     for (int tok = lbid() * 8 + wid; tok < S; tok += gridDim.x * 8) {
;       const int qt = tok >> 8, r = tok & 255;
;       const int slot0 = hs ? (qt * NCH3) : (64 * NCH3 + qt * NCH2);
;       float o1a = 0.f, o1b = 0.f, o2a = 0.f, o2b = 0.f, l1 = 0.f, l2 = 0.f;
;       for (int c = 0; c < nch; ++c) {
;         const char* sl = p.ws + OFF_SPL + (size_t)(slot0 + c) * SLOT_BYTES;
;         const unsigned v1 = *(const unsigned*)(sl + r * 128 + dq * 4);
;         const unsigned v2 = *(const unsigned*)(sl + 32768 + r * 128 + dq * 4);
;         const float2 lv = *(const float2*)(sl + 65536 + r * 8);
;         o1a += bflo(v1); o1b += bfhi(v1);
;         o2a += bflo(v2); o2b += bfhi(v2);
;         l1 += lv.x; l2 += lv.y;
.LBB0_656:
	s_or_b64 exec, exec, s[0:1]
	v_and_b32_e32 v5, 31, v6
	v_lshlrev_b32_e32 v0, 3, v5
	global_load_dwordx2 v[0:1], v0, s[20:21] offset:256
	ds_bpermute_b32 v7, v159, v3
	ds_bpermute_b32 v8, v159, v2
	v_ashrrev_i32_e32 v9, 6, v6
	s_mov_b32 s0, s92
	s_waitcnt lgkmcnt(1)
	v_add_f32_e32 v3, v3, v7
	s_waitcnt lgkmcnt(0)
	v_add_f32_e32 v2, v2, v8
	ds_bpermute_b32 v7, v160, v3
	ds_bpermute_b32 v8, v160, v2
	v_lshl_add_u32 v10, s0, 3, v9
	s_movk_i32 s0, 0x4000
	v_cmp_gt_i32_e32 vcc, s0, v10
	s_waitcnt lgkmcnt(1)
	v_add_f32_e32 v3, v3, v7
	s_waitcnt lgkmcnt(0)
	v_add_f32_e32 v2, v2, v8
	ds_bpermute_b32 v7, v161, v3
	ds_bpermute_b32 v8, v161, v2
	s_waitcnt lgkmcnt(1)
	v_add_f32_e32 v3, v3, v7
	s_waitcnt lgkmcnt(0)
	v_add_f32_e32 v2, v2, v8
	ds_bpermute_b32 v7, v162, v3
	ds_bpermute_b32 v8, v162, v2
	s_waitcnt lgkmcnt(1)
	v_add_f32_e32 v3, v3, v7
	s_waitcnt lgkmcnt(0)
	v_add_f32_e32 v2, v2, v8
	ds_bpermute_b32 v7, v163, v3
	ds_bpermute_b32 v8, v163, v2
	s_waitcnt lgkmcnt(1)
	v_add_f32_e32 v6, v3, v7
	s_waitcnt lgkmcnt(0)
	v_add_f32_e32 v2, v2, v8
	ds_bpermute_b32 v7, v164, v6
	ds_bpermute_b32 v3, v164, v2
	s_and_saveexec_b64 s[4:5], vcc
	s_cbranch_execz .LBB0_659
	s_waitcnt lgkmcnt(1)
	v_add_f32_e32 v6, v6, v7
	s_mov_b32 s0, 0x3fb8aa3b
	v_mul_f32_e32 v7, 0x3fb8aa3b, v6
	v_fma_f32 v8, v6, s0, -v7
	v_rndne_f32_e32 v9, v7
	v_fmac_f32_e32 v8, 0x32a5705f, v6
	v_sub_f32_e32 v7, v7, v9
	v_add_f32_e32 v7, v7, v8
	v_exp_f32_e32 v7, v7
	v_cvt_i32_f32_e32 v8, v9
	s_waitcnt lgkmcnt(0)
	v_add_f32_e32 v2, v2, v3
	s_mov_b32 s1, 0xc2ce8ed0
	v_cmp_ngt_f32_e32 vcc, s1, v6
	v_ldexp_f32 v3, v7, v8
	v_mul_f32_e32 v7, 0x3fb8aa3b, v2
	v_fma_f32 v8, v2, s0, -v7
	v_rndne_f32_e32 v11, v7
	v_fmac_f32_e32 v8, 0x32a5705f, v2
	v_sub_f32_e32 v7, v7, v11
	v_add_f32_e32 v7, v7, v8
	v_exp_f32_e32 v7, v7
	v_cvt_i32_f32_e32 v8, v11
	s_mov_b32 s6, 0x42b17218
	v_cndmask_b32_e32 v3, 0, v3, vcc
	v_mov_b32_e32 v11, 0x7f800000
	v_cmp_nlt_f32_e32 vcc, s6, v6
	v_ldexp_f32 v6, v7, v8
	v_lshlrev_b32_e32 v9, 1, v5
	v_cndmask_b32_e32 v3, v11, v3, vcc
	v_cmp_ngt_f32_e32 vcc, s1, v2
	v_and_b32_e32 v4, 0x80, v4
	s_lshl_b32 s10, s11, 3
	v_cndmask_b32_e32 v6, 0, v6, vcc
	v_cmp_nlt_f32_e32 vcc, s6, v2
	s_mov_b64 s[6:7], 0
	s_mov_b32 s18, 0x10800
	v_cndmask_b32_e32 v2, v11, v6, vcc
	v_sub_f32_e32 v2, v3, v2
	v_add_f32_e32 v11, 0x3eb60549, v2
	v_lshlrev_b32_e32 v2, 2, v5
	v_mov_b32_e32 v5, 0
	v_lshl_add_u64 v[6:7], s[26:27], 0, v[4:5]
	v_lshlrev_b32_e32 v4, 1, v9
	v_mov_b32_e32 v3, v5
	v_lshl_add_u64 v[6:7], v[6:7], 0, v[4:5]
	v_mov_b64_e32 v[8:9], s[16:17]
	s_mov_b32 s16, 0x8000
	s_mov_b32 s17, 0x10000
	v_mov_b32_e32 v12, 0x358637bd
	s_mov_b32 s19, 0x800000
	s_movk_i32 s20, 0x880
	s_movk_i32 s21, 0x3fff
	v_mov_b32_e32 v13, 7
	v_mov_b32_e32 v14, 3
	v_mov_b32_e32 v105, v5
	v_ashrrev_i32_e32 v115, 7, v10
	v_and_b32_e32 v115, -2, v115
	v_add_u32_e32 v118, 0x80, v115
	v_cndmask_b32_e64 v115, v115, v118, s[2:3]
	v_lshlrev_b32_sdwa v104, v13, v10 dst_sel:DWORD dst_unused:UNUSED_PAD src0_sel:DWORD src1_sel:BYTE_0
	s_nop 0
	v_mad_i64_i32 v[118:119], s[0:1], v115, s18, v[8:9]
	v_or_b32_e32 v115, 1, v115
	v_lshl_add_u64 v[120:121], v[118:119], 0, v[104:105]
	v_mad_i64_i32 v[122:123], s[0:1], v115, s18, v[8:9]
	v_lshl_add_u64 v[120:121], v[120:121], 0, v[2:3]
	v_lshlrev_b32_sdwa v116, v14, v10 dst_sel:DWORD dst_unused:UNUSED_PAD src0_sel:DWORD src1_sel:BYTE_0
	s_nop 0
	v_mov_b32_e32 v117, v105
	v_lshl_add_u64 v[124:125], v[122:123], 0, v[104:105]
	global_load_dword v104, v[120:121], off
	v_add_co_u32_e32 v120, vcc, 0x8000, v120
	v_lshl_add_u64 v[118:119], v[118:119], 0, v[116:117]
	s_nop 1
	v_addc_co_u32_e32 v121, vcc, 0, v121, vcc
	v_add_co_u32_e32 v118, vcc, 0x10000, v118
	v_lshl_add_u64 v[116:117], v[122:123], 0, v[116:117]
	v_lshl_add_u64 v[122:123], v[124:125], 0, v[2:3]
	s_nop 1
	v_addc_co_u32_e32 v119, vcc, 0, v119, vcc
	v_add_co_u32_e32 v124, vcc, s16, v122
	global_load_dword v115, v[120:121], off
	global_load_dwordx2 v[126:127], v[118:119], off
	global_load_dword v128, v[122:123], off
	s_nop 1
	v_addc_co_u32_e32 v125, vcc, 0, v123, vcc
	v_add_co_u32_e32 v116, vcc, s17, v116
	s_nop 1
	v_addc_co_u32_e32 v117, vcc, 0, v117, vcc
	global_load_dwordx2 v[118:119], v[116:117], off
	global_load_dword v129, v[124:125], off
	s_waitcnt vmcnt(0)
	s_branch .Lpl4_aw

; DI float bflo(unsigned u) { return __uint_as_float(u << 16); }
; DI float bfhi(unsigned u) { return __uint_as_float(u & 0xffff0000u); }
; DI int lbid() { int b = blockIdx.x; asm volatile("" : "+s"(b)); return b; }
; DI void combine_phase(const Params& p, int layer) {
;     ...
;     for (int tok = lbid() * 8 + wid; tok < S; tok += gridDim.x * 8) {
;       const int qt = tok >> 8, r = tok & 255;
;       const int slot0 = hs ? (qt * NCH3) : (64 * NCH3 + qt * NCH2);
;       float o1a = 0.f, o1b = 0.f, o2a = 0.f, o2b = 0.f, l1 = 0.f, l2 = 0.f;
;       for (int c = 0; c < nch; ++c) {
;         const char* sl = p.ws + OFF_SPL + (size_t)(slot0 + c) * SLOT_BYTES;
;         const unsigned v1 = *(const unsigned*)(sl + r * 128 + dq * 4);
;         const unsigned v2 = *(const unsigned*)(sl + 32768 + r * 128 + dq * 4);
;         const float2 lv = *(const float2*)(sl + 65536 + r * 8);
;         o1a += bflo(v1); o1b += bfhi(v1);
;         o2a += bflo(v2); o2b += bfhi(v2);
;         l1 += lv.x; l2 += lv.y;
;       }
;       const float i1 = 1.f / l1, i2 = lam / l2;
;       const float oa = o1a * i1 - o2a * i2, ob = o1b * i1 - o2b * i2;
;       float ss = oa * oa + ob * ob;
; #pragma unroll
;       for (int o = 1; o <= 16; o <<= 1) ss += __shfl_xor(ss, o);
;       const float rr = rsqrtf(ss * (1.f / 64.f) + EPS) * (1.f - lam_init);
;       *(unsigned*)(mixed + (size_t)tok * LDH + 384 + (2 + hs) * 64 + 2 * dq) = pack2(oa * rr * g0, ob * rr * g1);
;     }
.Lpl4_aw:
	v_ashrrev_i32_e32 v15, 7, v10
	v_and_b32_e32 v15, -2, v15
	v_add_u32_e32 v18, 0x80, v15
	v_cndmask_b32_e64 v15, v15, v18, s[2:3]
	v_lshlrev_b32_sdwa v4, v13, v10 dst_sel:DWORD dst_unused:UNUSED_PAD src0_sel:DWORD src1_sel:BYTE_0
	v_mad_i64_i32 v[18:19], s[0:1], v15, s18, v[8:9]
	v_or_b32_e32 v15, 1, v15
	v_lshl_add_u64 v[20:21], v[18:19], 0, v[4:5]
	v_mad_i64_i32 v[22:23], s[0:1], v15, s18, v[8:9]
	v_lshl_add_u64 v[20:21], v[20:21], 0, v[2:3]
	v_lshlrev_b32_sdwa v16, v14, v10 dst_sel:DWORD dst_unused:UNUSED_PAD src0_sel:DWORD src1_sel:BYTE_0
	v_mov_b32_e32 v17, v5
	v_lshl_add_u64 v[24:25], v[22:23], 0, v[4:5]
	v_mov_b32_e32 v4, v104
	v_add_co_u32_e32 v20, vcc, 0x8000, v20
	v_lshl_add_u64 v[18:19], v[18:19], 0, v[16:17]
	s_nop 0
	v_addc_co_u32_e32 v21, vcc, 0, v21, vcc
	v_add_co_u32_e32 v18, vcc, 0x10000, v18
	v_lshl_add_u64 v[16:17], v[22:23], 0, v[16:17]
	v_lshl_add_u64 v[22:23], v[24:25], 0, v[2:3]
	v_addc_co_u32_e32 v19, vcc, 0, v19, vcc
	v_add_co_u32_e32 v24, vcc, s16, v22
	v_mov_b32_e32 v15, v115
	v_mov_b64_e32 v[26:27], v[126:127]
	v_mov_b32_e32 v28, v128
	v_addc_co_u32_e32 v25, vcc, 0, v23, vcc
	v_add_co_u32_e32 v16, vcc, s17, v16
	v_lshlrev_b32_e32 v20, 16, v15
	v_addc_co_u32_e32 v17, vcc, 0, v17, vcc
	v_mov_b64_e32 v[18:19], v[118:119]
	v_mov_b32_e32 v29, v129
	v_lshlrev_b32_e32 v16, 16, v4
	v_and_b32_e32 v17, 0xffff0000, v4
	v_and_b32_e32 v21, 0xffff0000, v15
	v_add_f32_e32 v4, 0, v26
	v_add_f32_e32 v15, 0, v27
	v_pk_add_f32 v[20:21], v[20:21], 0 op_sel_hi:[1,0]
	v_pk_add_f32 v[16:17], v[16:17], 0 op_sel_hi:[1,0]
	v_lshlrev_b32_e32 v22, 16, v28
	v_and_b32_e32 v23, 0xffff0000, v28
	v_pk_add_f32 v[16:17], v[16:17], v[22:23]
	v_add_f32_e32 v4, v4, v18
	v_lshlrev_b32_e32 v24, 16, v29
	v_and_b32_e32 v25, 0xffff0000, v29
	v_add_f32_e32 v15, v15, v19
	v_pk_add_f32 v[18:19], v[20:21], v[24:25]
	v_div_scale_f32 v20, s[0:1], v4, v4, 1.0
	v_div_scale_f32 v22, s[0:1], v15, v15, v11
	v_rcp_f32_e32 v24, v20
	v_rcp_f32_e32 v25, v22
	v_div_scale_f32 v21, vcc, 1.0, v4, 1.0
	v_fma_f32 v26, -v20, v24, 1.0
	v_fma_f32 v27, -v22, v25, 1.0
	v_fmac_f32_e32 v24, v26, v24
	v_div_scale_f32 v23, s[0:1], v11, v15, v11
	v_fmac_f32_e32 v25, v27, v25
	v_mul_f32_e32 v26, v21, v24
	v_mul_f32_e32 v27, v23, v25
	v_fma_f32 v28, -v20, v26, v21
	v_fma_f32 v29, -v22, v27, v23
	v_fmac_f32_e32 v26, v28, v24
	v_fmac_f32_e32 v27, v29, v25
	v_fma_f32 v20, -v20, v26, v21
	v_fma_f32 v21, -v22, v27, v23
	v_div_fmas_f32 v20, v20, v24, v26
	s_mov_b64 vcc, s[0:1]
	v_div_fixup_f32 v4, v20, v4, 1.0
	v_div_fmas_f32 v20, v21, v25, v27
	v_div_fixup_f32 v20, v20, v15, v11
	v_pk_mul_f32 v[18:19], v[18:19], v[20:21] op_sel_hi:[1,0]
	s_nop 0
	v_pk_fma_f32 v[16:17], v[16:17], v[4:5], v[18:19] op_sel_hi:[1,0,1] neg_lo:[0,0,1] neg_hi:[0,0,1]
	s_nop 0
	v_pk_mul_f32 v[18:19], v[16:17], v[16:17]
	s_nop 0
	v_add_f32_e32 v4, v18, v19
	ds_bpermute_b32 v15, v164, v4
	v_mad_i64_i32 v[18:19], s[0:1], v10, s20, v[6:7]
	v_add_u32_e32 v10, s10, v10
	v_cmp_lt_i32_e64 s[0:1], s21, v10
	s_waitcnt lgkmcnt(0)
	v_add_f32_e32 v4, v4, v15
	ds_bpermute_b32 v15, v163, v4
	s_or_b64 s[6:7], s[0:1], s[6:7]
	s_mov_b64 s[98:99], exec
	s_andn2_b64 exec, exec, s[6:7]
	s_cbranch_execz .Lpl4_np
	v_mov_b32_e32 v105, v5
	v_ashrrev_i32_e32 v115, 7, v10
	v_and_b32_e32 v115, -2, v115
	v_add_u32_e32 v118, 0x80, v115
	v_cndmask_b32_e64 v115, v115, v118, s[2:3]
	v_lshlrev_b32_sdwa v104, v13, v10 dst_sel:DWORD dst_unused:UNUSED_PAD src0_sel:DWORD src1_sel:BYTE_0
	s_nop 0
	v_mad_i64_i32 v[118:119], s[0:1], v115, s18, v[8:9]
	v_or_b32_e32 v115, 1, v115
	v_lshl_add_u64 v[120:121], v[118:119], 0, v[104:105]
	v_mad_i64_i32 v[122:123], s[0:1], v115, s18, v[8:9]
	v_lshl_add_u64 v[120:121], v[120:121], 0, v[2:3]
	v_lshlrev_b32_sdwa v116, v14, v10 dst_sel:DWORD dst_unused:UNUSED_PAD src0_sel:DWORD src1_sel:BYTE_0
	s_nop 0
	v_mov_b32_e32 v117, v105
	v_lshl_add_u64 v[124:125], v[122:123], 0, v[104:105]
	global_load_dword v104, v[120:121], off
	v_add_co_u32_e32 v120, vcc, 0x8000, v120
	v_lshl_add_u64 v[118:119], v[118:119], 0, v[116:117]
	s_nop 1
	v_addc_co_u32_e32 v121, vcc, 0, v121, vcc
	v_add_co_u32_e32 v118, vcc, 0x10000, v118
	v_lshl_add_u64 v[116:117], v[122:123], 0, v[116:117]
	v_lshl_add_u64 v[122:123], v[124:125], 0, v[2:3]
	s_nop 1
	v_addc_co_u32_e32 v119, vcc, 0, v119, vcc
	v_add_co_u32_e32 v124, vcc, s16, v122
	global_load_dword v115, v[120:121], off
	global_load_dwordx2 v[126:127], v[118:119], off
	global_load_dword v128, v[122:123], off
	s_nop 1
	v_addc_co_u32_e32 v125, vcc, 0, v123, vcc
	v_add_co_u32_e32 v116, vcc, s17, v116
	s_nop 1
	v_addc_co_u32_e32 v117, vcc, 0, v117, vcc
	global_load_dwordx2 v[118:119], v[116:117], off
	global_load_dword v129, v[124:125], off
.Lpl4_np:
	s_mov_b64 exec, s[98:99]
	s_waitcnt lgkmcnt(0)
	v_add_f32_e32 v4, v4, v15
	ds_bpermute_b32 v15, v162, v4
	s_waitcnt lgkmcnt(0)
	v_add_f32_e32 v4, v4, v15
	ds_bpermute_b32 v15, v161, v4
	s_waitcnt lgkmcnt(0)
	v_add_f32_e32 v4, v4, v15
	ds_bpermute_b32 v15, v160, v4
	s_waitcnt lgkmcnt(0)
	v_add_f32_e32 v4, v4, v15
	v_fmamk_f32 v4, v4, 0x3c800000, v12
	v_mul_f32_e32 v15, 0x4b800000, v4
	v_cmp_gt_f32_e32 vcc, s19, v4
	s_nop 1
	v_cndmask_b32_e32 v4, v4, v15, vcc
	v_rsq_f32_e32 v4, v4
	s_nop 0
	v_mul_f32_e32 v15, 0x45800000, v4
	v_cndmask_b32_e32 v4, v4, v15, vcc
	v_mul_f32_e32 v4, 0x3f24fd5c, v4
	v_pk_mul_f32 v[16:17], v[16:17], v[4:5] op_sel_hi:[1,0]
	s_nop 0
	v_pk_mul_f32 v[16:17], v[0:1], v[16:17]
	s_nop 0
	v_cvt_pk_bf16_f32 v4, v16, v17
	global_store_dword v[18:19], v4, off offset:1024
	s_andn2_b64 exec, exec, s[6:7]
	s_cbranch_execnz .Lpl4_top

; #define PG8_STAGE(bufoff, gbase, voff) do { _Pragma("unroll") for (int _i = 0; _i < 2; ++_i) \
;         __builtin_amdgcn_global_load_lds((const unsigned*)((const char*)(gbase) + (voff)[_i]), (PG8_LAS unsigned*)(lds + (bufoff) + ldsw + _i * 8192), 16, 0, 0); } while (0)
; #define PG8_LDA(dst, b, h) do { _Pragma("unroll") for (int m = 0; m < 4; ++m) _Pragma("unroll") for (int k = 0; k < 2; ++k) dst[m][k] = *(const PG8_LAS bf16x8*)(lds + PG8_SA(b, h) + aoff + m * 2048 + k * 1024); } while (0)
; template <class Epi, class Sched, bool STAMP = false>
; __device__ __forceinline__ void gemm_phase(PG8_LAS unsigned char* lds, const Gemm g, const Sched& S, const Epi& E, unsigned long long* stamps) {
;     ...
;         for (int t = 0; t < nt; t += 2) {
;             const bool last = (t == nt - 2);
;             const char* a1 = cA + (size_t)(t + 1) * kstep;
;             const char* a2 = last ? nA : cA + (size_t)(t + 2) * kstep; const char* b2 = last ? nB : cB + (size_t)(t + 2) * kstep;
;             const char* a3 = a2 + kstep; const char* b3 = b2 + kstep;
;             if (last && has_next) S.a_ready(nxt);
;             PG8_LDB(B0, 0, 0); PG8_SCHED; PG8_LDA(At, 0, 0); PG8_STAGE(PG8_SA(1, 1), a1 + hstep, voffA);
;             PG8_WAIT_L(8); PG8_BAR; PG8_WAIT_L(0); PG8_MMA(0, 0, At, B0); PG8_BAR; PG8_SCHED;
;             PG8_LDB(B1, 0, 1); PG8_STAGE(PG8_SB(0, 0), b2, voffB);
;             PG8_BAR; PG8_WAIT_L(0); PG8_MMA(0, 1, At, B1); PG8_BAR;
;             PG8_LDA(At, 0, 1); PG8_STAGE(PG8_SA(0, 0), a2, voffA);
;             PG8_BAR; PG8_WAIT_L(0); PG8_MMA(1, 0, At, B0); PG8_BAR; PG8_SCHED;
;             PG8_STAGE(PG8_SB(0, 1), b2 + hstep, voffB);
;             PG8_WAIT_V(6); PG8_BAR; PG8_MMA(1, 1, At, B1); PG8_BAR;
;             PG8_LDB(B0, 1, 0); PG8_SCHED; PG8_LDA(At, 1, 0); PG8_STAGE(PG8_SA(0, 1), a2 + hstep, voffA);
;             PG8_WAIT_L(8); PG8_BAR; PG8_WAIT_L(0); PG8_MMA(0, 0, At, B0); PG8_BAR; PG8_SCHED;
;             PG8_LDB(B1, 1, 1); PG8_STAGE(PG8_SB(1, 0), b3, voffB);
;             PG8_BAR; PG8_WAIT_L(0); PG8_MMA(0, 1, At, B1); PG8_BAR;
;             PG8_LDA(At, 1, 1); PG8_STAGE(PG8_SA(1, 0), a3, voffA);
;             PG8_BAR; PG8_WAIT_L(0); PG8_MMA(1, 0, At, B0); PG8_BAR; PG8_SCHED;
;             PG8_STAGE(PG8_SB(1, 1), b3 + hstep, voffB);
;             PG8_WAIT_V(6); PG8_BAR; PG8_MMA(1, 1, At, B1); PG8_BAR;
;         }
.Lgu4_half_loop:
	ds_read_b128 v[140:143], v147
	ds_read_b128 v[170:173], v148
	ds_read_b128 v[174:177], v149
	ds_read_b128 v[178:181], v150
	s_add_u32 s18, s16, 0x100
	s_addc_u32 s19, s17, 0
	s_cmp_eq_u32 s10, 12
	s_cselect_b32 s29, s5, s19
	s_cselect_b32 s28, s4, s18
	s_cselect_b32 s21, s1, s63
	s_cselect_b32 s20, s0, s62
	s_mov_b32 m0, s55
	ds_read_b128 v[182:185], v145
	ds_read_b128 v[186:189], v145 offset:1024
	ds_read_b128 v[190:193], v145 offset:2048
	ds_read_b128 v[194:197], v145 offset:3072
	ds_read_b128 v[198:201], v145 offset:4096
	ds_read_b128 v[202:205], v145 offset:5120
	ds_read_b128 v[206:209], v145 offset:6144
	ds_read_b128 v[210:213], v145 offset:7168
	global_load_lds_dwordx4 v132, s[16:17]
	s_mov_b32 m0, s56
	s_nop 0
	global_load_lds_dwordx4 v134, s[16:17]
	s_waitcnt lgkmcnt(8)
	s_barrier
	s_waitcnt lgkmcnt(0)
	s_setprio 1
	s_waitcnt lgkmcnt(0)
	v_mfma_f32_16x16x32_bf16 v[124:127], v[140:143], v[182:185], v[124:127]
	v_mfma_f32_16x16x32_bf16 v[120:123], v[174:177], v[182:185], v[120:123]
	v_mfma_f32_16x16x32_bf16 v[108:111], v[140:143], v[190:193], v[108:111]
	v_mfma_f32_16x16x32_bf16 v[104:107], v[174:177], v[190:193], v[104:107]
	v_mfma_f32_16x16x32_bf16 v[92:95], v[140:143], v[198:201], v[92:95]
	v_mfma_f32_16x16x32_bf16 v[88:91], v[174:177], v[198:201], v[88:91]
	v_mfma_f32_16x16x32_bf16 v[76:79], v[140:143], v[206:209], v[76:79]
	v_mfma_f32_16x16x32_bf16 v[72:75], v[174:177], v[206:209], v[72:75]
	v_mfma_f32_16x16x32_bf16 v[124:127], v[170:173], v[186:189], v[124:127]
	v_mfma_f32_16x16x32_bf16 v[120:123], v[178:181], v[186:189], v[120:123]
	v_mfma_f32_16x16x32_bf16 v[108:111], v[170:173], v[194:197], v[108:111]
	v_mfma_f32_16x16x32_bf16 v[104:107], v[178:181], v[194:197], v[104:107]
	v_mfma_f32_16x16x32_bf16 v[92:95], v[170:173], v[202:205], v[92:95]
	v_mfma_f32_16x16x32_bf16 v[88:91], v[178:181], v[202:205], v[88:91]
	v_mfma_f32_16x16x32_bf16 v[76:79], v[170:173], v[210:213], v[76:79]
	v_mfma_f32_16x16x32_bf16 v[72:75], v[178:181], v[210:213], v[72:75]
	s_setprio 0
	s_barrier
	s_mov_b32 m0, s37
	s_nop 0
	global_load_lds_dwordx4 v130, s[20:21]
	s_mov_b32 m0, s40
	s_nop 0
	global_load_lds_dwordx4 v128, s[20:21]
	s_barrier
	s_waitcnt lgkmcnt(0)
	s_setprio 1
	s_waitcnt lgkmcnt(0)
	s_setprio 0
	s_mov_b32 m0, s34
	s_barrier
	ds_read_b128 v[182:185], v145 offset:16384
	ds_read_b128 v[186:189], v145 offset:17408
	ds_read_b128 v[190:193], v145 offset:18432
	ds_read_b128 v[194:197], v145 offset:19456
	ds_read_b128 v[198:201], v145 offset:20480
	ds_read_b128 v[202:205], v145 offset:21504
	ds_read_b128 v[206:209], v145 offset:22528
	ds_read_b128 v[210:213], v145 offset:23552
	global_load_lds_dwordx4 v130, s[28:29]
	s_mov_b32 m0, s41
	s_nop 0
	global_load_lds_dwordx4 v128, s[28:29]
	s_barrier
	s_waitcnt lgkmcnt(0)
	s_setprio 1
	s_waitcnt lgkmcnt(0)
	v_mfma_f32_16x16x32_bf16 v[60:63], v[140:143], v[182:185], v[60:63]
	v_mfma_f32_16x16x32_bf16 v[56:59], v[174:177], v[182:185], v[56:59]
	v_mfma_f32_16x16x32_bf16 v[44:47], v[140:143], v[190:193], v[44:47]
	v_mfma_f32_16x16x32_bf16 v[40:43], v[174:177], v[190:193], v[40:43]
	v_mfma_f32_16x16x32_bf16 v[28:31], v[140:143], v[198:201], v[28:31]
	v_mfma_f32_16x16x32_bf16 v[24:27], v[174:177], v[198:201], v[24:27]
	v_mfma_f32_16x16x32_bf16 v[12:15], v[140:143], v[206:209], v[12:15]
	v_mfma_f32_16x16x32_bf16 v[8:11], v[174:177], v[206:209], v[8:11]
	v_mfma_f32_16x16x32_bf16 v[60:63], v[170:173], v[186:189], v[60:63]
	v_mfma_f32_16x16x32_bf16 v[56:59], v[178:181], v[186:189], v[56:59]
	v_mfma_f32_16x16x32_bf16 v[44:47], v[170:173], v[194:197], v[44:47]
	v_mfma_f32_16x16x32_bf16 v[40:43], v[178:181], v[194:197], v[40:43]
	v_mfma_f32_16x16x32_bf16 v[28:31], v[170:173], v[202:205], v[28:31]
	v_mfma_f32_16x16x32_bf16 v[24:27], v[178:181], v[202:205], v[24:27]
	v_mfma_f32_16x16x32_bf16 v[12:15], v[170:173], v[210:213], v[12:15]
	v_mfma_f32_16x16x32_bf16 v[8:11], v[178:181], v[210:213], v[8:11]
	s_setprio 0
	s_barrier
	s_add_u32 s16, s20, 0x44000
	s_addc_u32 s17, s21, 0
	s_mov_b32 m0, s42
	s_nop 0
	s_mov_b32 m0, s43
	s_nop 0
	s_waitcnt vmcnt(4)
	s_barrier
	s_setprio 1
	s_setprio 0
	s_barrier
	ds_read_b128 v[140:143], v155
	ds_read_b128 v[170:173], v156
	ds_read_b128 v[174:177], v157
	ds_read_b128 v[178:181], v165
	s_add_u32 s16, s28, 0x44000
	s_addc_u32 s17, s29, 0
	s_mov_b32 m0, s44
	ds_read_b128 v[182:185], v145 offset:32768
	ds_read_b128 v[186:189], v145 offset:33792
	ds_read_b128 v[190:193], v145 offset:34816
	ds_read_b128 v[194:197], v145 offset:35840
	ds_read_b128 v[198:201], v145 offset:36864
	ds_read_b128 v[202:205], v145 offset:37888
	ds_read_b128 v[206:209], v145 offset:38912
	ds_read_b128 v[210:213], v145 offset:39936
	global_load_lds_dwordx4 v130, s[16:17]
	s_mov_b32 m0, s45
	s_nop 0
	global_load_lds_dwordx4 v128, s[16:17]
	s_waitcnt lgkmcnt(8)
	s_barrier
	s_waitcnt lgkmcnt(0)
	s_setprio 1
	s_waitcnt lgkmcnt(0)
	v_mfma_f32_16x16x32_bf16 v[124:127], v[140:143], v[182:185], v[124:127]
	v_mfma_f32_16x16x32_bf16 v[120:123], v[174:177], v[182:185], v[120:123]
	v_mfma_f32_16x16x32_bf16 v[108:111], v[140:143], v[190:193], v[108:111]
	v_mfma_f32_16x16x32_bf16 v[104:107], v[174:177], v[190:193], v[104:107]
	v_mfma_f32_16x16x32_bf16 v[92:95], v[140:143], v[198:201], v[92:95]
	v_mfma_f32_16x16x32_bf16 v[88:91], v[174:177], v[198:201], v[88:91]
	v_mfma_f32_16x16x32_bf16 v[76:79], v[140:143], v[206:209], v[76:79]
	v_mfma_f32_16x16x32_bf16 v[72:75], v[174:177], v[206:209], v[72:75]
	v_mfma_f32_16x16x32_bf16 v[124:127], v[170:173], v[186:189], v[124:127]
	v_mfma_f32_16x16x32_bf16 v[120:123], v[178:181], v[186:189], v[120:123]
	v_mfma_f32_16x16x32_bf16 v[108:111], v[170:173], v[194:197], v[108:111]
	v_mfma_f32_16x16x32_bf16 v[104:107], v[178:181], v[194:197], v[104:107]
	v_mfma_f32_16x16x32_bf16 v[92:95], v[170:173], v[202:205], v[92:95]
	v_mfma_f32_16x16x32_bf16 v[88:91], v[178:181], v[202:205], v[88:91]
	v_mfma_f32_16x16x32_bf16 v[76:79], v[170:173], v[210:213], v[76:79]
	v_mfma_f32_16x16x32_bf16 v[72:75], v[178:181], v[210:213], v[72:75]
	s_setprio 0
	s_barrier
; #define PG8_STAGE(bufoff, gbase, voff) do { _Pragma("unroll") for (int _i = 0; _i < 2; ++_i) \
;         __builtin_amdgcn_global_load_lds((const unsigned*)((const char*)(gbase) + (voff)[_i]), (PG8_LAS unsigned*)(lds + (bufoff) + ldsw + _i * 8192), 16, 0, 0); } while (0)
; #define PG8_LDA(dst, b, h) do { _Pragma("unroll") for (int m = 0; m < 4; ++m) _Pragma("unroll") for (int k = 0; k < 2; ++k) dst[m][k] = *(const PG8_LAS bf16x8*)(lds + PG8_SA(b, h) + aoff + m * 2048 + k * 1024); } while (0)
; #define PG8_LDB(dst, b, h) do { _Pragma("unroll") for (int n = 0; n < 2; ++n) _Pragma("unroll") for (int k = 0; k < 2; ++k) dst[n][k] = *(const PG8_LAS bf16x8*)(lds + PG8_SB(b, h) + boff + n * 2048 + k * 1024); } while (0)
; #define PG8_MMA(ai, bj, At, Bt) do { __builtin_amdgcn_s_setprio(1); _Pragma("unroll") for (int m = 0; m < 4; ++m) _Pragma("unroll") for (int n = 0; n < 2; ++n) _Pragma("unroll") for (int k = 0; k < 2; ++k) \
;         acc[ai][bj][m][n] = __builtin_amdgcn_mfma_f32_16x16x32_bf16(Bt[n][k], At[m][k], acc[ai][bj][m][n], 0, 0, 0); __builtin_amdgcn_s_setprio(0); } while (0)
; #define PG8_WAIT_V(n) asm volatile("s_waitcnt vmcnt(" #n ")" ::: "memory")
; #define PG8_WAIT_L(n) asm volatile("s_waitcnt lgkmcnt(" #n ")" ::: "memory")
; #define PG8_BAR __builtin_amdgcn_s_barrier()
; #define PG8_SCHED __builtin_amdgcn_sched_barrier(0)
; template <class Epi, class Sched, bool STAMP = false>
; __device__ __forceinline__ void gemm_phase(PG8_LAS unsigned char* lds, const Gemm g, const Sched& S, const Epi& E, unsigned long long* stamps) {
;     ...
;             PG8_LDB(B0, 1, 0); PG8_SCHED; PG8_LDA(At, 1, 0); PG8_STAGE(PG8_SA(0, 1), a2 + hstep, voffA);
;             PG8_WAIT_L(8); PG8_BAR; PG8_WAIT_L(0); PG8_MMA(0, 0, At, B0); PG8_BAR; PG8_SCHED;
;             PG8_LDB(B1, 1, 1); PG8_STAGE(PG8_SB(1, 0), b3, voffB);
;             PG8_BAR; PG8_WAIT_L(0); PG8_MMA(0, 1, At, B1); PG8_BAR;
;             PG8_LDA(At, 1, 1); PG8_STAGE(PG8_SA(1, 0), a3, voffA);
;             PG8_BAR; PG8_WAIT_L(0); PG8_MMA(1, 0, At, B0); PG8_BAR; PG8_SCHED;
;             PG8_STAGE(PG8_SB(1, 1), b3 + hstep, voffB);
;             PG8_WAIT_V(6); PG8_BAR; PG8_MMA(1, 1, At, B1); PG8_BAR;
;         }
	s_mov_b32 m0, s48
	s_add_u32 s100, s20, 0x80
	s_addc_u32 s101, s21, 0
	global_load_lds_dwordx4 v130, s[100:101]
	s_mov_b32 m0, s49
	s_nop 0
	global_load_lds_dwordx4 v128, s[100:101]
	s_barrier
	s_waitcnt lgkmcnt(0)
	s_setprio 1
	s_waitcnt lgkmcnt(0)
	s_setprio 0
	s_mov_b32 m0, s50
	s_barrier
	ds_read_b128 v[182:185], v145 offset:49152
	ds_read_b128 v[186:189], v145 offset:50176
	ds_read_b128 v[190:193], v145 offset:51200
	ds_read_b128 v[194:197], v145 offset:52224
	ds_read_b128 v[198:201], v145 offset:53248
	ds_read_b128 v[202:205], v145 offset:54272
	ds_read_b128 v[206:209], v145 offset:55296
	ds_read_b128 v[210:213], v145 offset:56320
	s_add_u32 s100, s28, 0x80
	s_addc_u32 s101, s29, 0
	global_load_lds_dwordx4 v130, s[100:101]
	s_mov_b32 m0, s51
	s_nop 0
	global_load_lds_dwordx4 v128, s[100:101]
	s_barrier
	s_waitcnt lgkmcnt(0)
	s_setprio 1
	s_waitcnt lgkmcnt(0)
	v_mfma_f32_16x16x32_bf16 v[60:63], v[140:143], v[182:185], v[60:63]
	v_mfma_f32_16x16x32_bf16 v[56:59], v[174:177], v[182:185], v[56:59]
	v_mfma_f32_16x16x32_bf16 v[44:47], v[140:143], v[190:193], v[44:47]
	v_mfma_f32_16x16x32_bf16 v[40:43], v[174:177], v[190:193], v[40:43]
	v_mfma_f32_16x16x32_bf16 v[28:31], v[140:143], v[198:201], v[28:31]
	v_mfma_f32_16x16x32_bf16 v[24:27], v[174:177], v[198:201], v[24:27]
	v_mfma_f32_16x16x32_bf16 v[12:15], v[140:143], v[206:209], v[12:15]
	v_mfma_f32_16x16x32_bf16 v[8:11], v[174:177], v[206:209], v[8:11]
	v_mfma_f32_16x16x32_bf16 v[60:63], v[170:173], v[186:189], v[60:63]
	v_mfma_f32_16x16x32_bf16 v[56:59], v[178:181], v[186:189], v[56:59]
	v_mfma_f32_16x16x32_bf16 v[44:47], v[170:173], v[194:197], v[44:47]
	v_mfma_f32_16x16x32_bf16 v[40:43], v[178:181], v[194:197], v[40:43]
	v_mfma_f32_16x16x32_bf16 v[28:31], v[170:173], v[202:205], v[28:31]
	v_mfma_f32_16x16x32_bf16 v[24:27], v[178:181], v[202:205], v[24:27]
	v_mfma_f32_16x16x32_bf16 v[12:15], v[170:173], v[210:213], v[12:15]
	v_mfma_f32_16x16x32_bf16 v[8:11], v[178:181], v[210:213], v[8:11]
	s_setprio 0
	s_barrier
	s_add_u32 s16, s20, 0x44080
	s_addc_u32 s17, s21, 0
	s_mov_b32 m0, s52
	s_nop 0
	s_mov_b32 m0, s53
	s_nop 0
	s_waitcnt vmcnt(4)
	s_barrier
	s_setprio 1
	s_setprio 0
	s_add_i32 s10, s10, 2
	s_add_u32 s62, s62, 0x100
	s_addc_u32 s63, s63, 0
	s_cmp_gt_u32 s10, 13
	s_mov_b64 s[16:17], s[18:19]
	s_barrier
	s_cbranch_scc0 .Lgu4_half_loop
; DI float ex2(float x) { return __builtin_amdgcn_exp2f(x); }
;     DI void operator()(const f32x4 (&acc)[2][2][4][2], const Unit& u, int wr, int wc, int fr, int fq) const {
;         const int row0 = u.pm * BM + wr * 64 + fr, hcol0 = ((u.pn * BM + wc * 32) >> 1) + 4 * fq;
; #pragma unroll
;         for (int ai = 0; ai < 2; ++ai)
; #pragma unroll
;             for (int m = 0; m < 4; ++m) { u16* rowp = O + (size_t)(row0 + ai * HALF + m * 16) * ldc + hcol0;
; #pragma unroll
;                 for (int bj = 0; bj < 2; ++bj) { const f32x4 g = acc[ai][bj][m][0], up = acc[ai][bj][m][1]; float r[4];
; #pragma unroll
;                     for (int j = 0; j < 4; ++j) r[j] = g[j] * up[j] * __builtin_amdgcn_rcpf(1.f + ex2(-LOG2E * g[j]));
;                     uint2 w = {pack2(r[0], r[1]), pack2(r[2], r[3])}; *(uint2*)(rowp + bj * (HALF / 2)) = w; } }
;     }
	v_exp_f32_e64 v171, -v124
	v_exp_f32_e64 v175, -v125
	s_lshl_b32 s10, s61, 8
	v_add_f32_e32 v171, 1.0, v171
	v_rcp_f32_e32 v174, v171
	v_add_f32_e32 v171, 1.0, v175
	v_exp_f32_e64 v176, -v126
	v_exp_f32_e64 v177, -v127
	v_rcp_f32_e32 v175, v171
	v_add_f32_e32 v171, 1.0, v176
	v_rcp_f32_e32 v176, v171
	v_add_f32_e32 v171, 1.0, v177
	v_rcp_f32_e32 v177, v171
	v_pk_mul_f32 v[122:123], v[126:127], v[122:123]
	v_pk_mul_f32 v[120:121], v[124:125], v[120:121]
	s_or_b32 s10, s10, s47
	s_or_b32 s10, s10, s98
	v_pk_mul_f32 v[120:121], v[120:121], v[174:175]
	v_pk_mul_f32 v[122:123], v[122:123], v[176:177]
	s_ashr_i32 s10, s10, 1
	v_cvt_pk_bf16_f32 v120, v120, v121
	v_cvt_pk_bf16_f32 v121, v122, v123
	v_or_b32_e32 v140, s10, v146
	v_lshl_add_u32 v170, s60, 8, v144
	v_ashrrev_i32_e32 v141, 31, v140
	v_mov_b64_e32 v[142:143], s[12:13]
	v_mad_i64_i32 v[172:173], s[16:17], v170, s57, v[142:143]
	v_lshlrev_b64 v[140:141], 1, v[140:141]
	v_lshl_add_u64 v[172:173], v[172:173], 0, v[140:141]
	global_store_dwordx2 v[172:173], v[120:121], off
	v_exp_f32_e64 v114, -v108
	v_exp_f32_e64 v115, -v109
	v_exp_f32_e64 v116, -v110
	v_exp_f32_e64 v117, -v111
	v_add_f32_e32 v114, 1.0, v114
	v_add_f32_e32 v115, 1.0, v115
	v_add_f32_e32 v116, 1.0, v116
	v_add_f32_e32 v117, 1.0, v117
	v_rcp_f32_e32 v114, v114
	v_rcp_f32_e32 v115, v115
	v_rcp_f32_e32 v116, v116
	v_rcp_f32_e32 v117, v117
	v_pk_mul_f32 v[106:107], v[110:111], v[106:107]
	v_pk_mul_f32 v[104:105], v[108:109], v[104:105]
	v_pk_mul_f32 v[104:105], v[104:105], v[114:115]
	v_pk_mul_f32 v[106:107], v[106:107], v[116:117]
	v_cvt_pk_bf16_f32 v104, v104, v105
	v_cvt_pk_bf16_f32 v105, v106, v107
	v_or_b32_e32 v112, 16, v170
	v_mad_i64_i32 v[112:113], s[16:17], v112, s57, v[142:143]
	v_lshl_add_u64 v[112:113], v[112:113], 0, v[140:141]
	global_store_dwordx2 v[112:113], v[104:105], off
	v_exp_f32_e64 v98, -v92
	v_exp_f32_e64 v99, -v93
	v_exp_f32_e64 v100, -v94
	v_exp_f32_e64 v101, -v95
	v_add_f32_e32 v98, 1.0, v98
	v_add_f32_e32 v99, 1.0, v99
	v_add_f32_e32 v100, 1.0, v100
	v_add_f32_e32 v101, 1.0, v101
	v_rcp_f32_e32 v98, v98
	v_rcp_f32_e32 v99, v99
	v_rcp_f32_e32 v100, v100
	v_rcp_f32_e32 v101, v101
	v_pk_mul_f32 v[90:91], v[94:95], v[90:91]
	v_pk_mul_f32 v[88:89], v[92:93], v[88:89]
	v_pk_mul_f32 v[88:89], v[88:89], v[98:99]
	v_pk_mul_f32 v[90:91], v[90:91], v[100:101]
	v_cvt_pk_bf16_f32 v88, v88, v89
	v_cvt_pk_bf16_f32 v89, v90, v91
	v_or_b32_e32 v96, 32, v170
	v_mad_i64_i32 v[96:97], s[16:17], v96, s57, v[142:143]
	v_lshl_add_u64 v[96:97], v[96:97], 0, v[140:141]
	global_store_dwordx2 v[96:97], v[88:89], off
	v_exp_f32_e64 v82, -v76
	v_exp_f32_e64 v83, -v77
	v_exp_f32_e64 v84, -v78
	v_exp_f32_e64 v85, -v79
	v_add_f32_e32 v82, 1.0, v82
	v_add_f32_e32 v83, 1.0, v83
	v_add_f32_e32 v84, 1.0, v84
	v_add_f32_e32 v85, 1.0, v85
	v_rcp_f32_e32 v82, v82
	v_rcp_f32_e32 v83, v83
	v_rcp_f32_e32 v84, v84
	v_rcp_f32_e32 v85, v85
	v_pk_mul_f32 v[74:75], v[78:79], v[74:75]
	v_pk_mul_f32 v[72:73], v[76:77], v[72:73]
	v_pk_mul_f32 v[72:73], v[72:73], v[82:83]
	v_pk_mul_f32 v[74:75], v[74:75], v[84:85]
	v_cvt_pk_bf16_f32 v72, v72, v73
	v_cvt_pk_bf16_f32 v73, v74, v75
	v_or_b32_e32 v80, 48, v170
	v_mad_i64_i32 v[80:81], s[16:17], v80, s57, v[142:143]
	v_lshl_add_u64 v[80:81], v[80:81], 0, v[140:141]
	global_store_dwordx2 v[80:81], v[72:73], off
	v_exp_f32_e64 v66, -v60
	v_exp_f32_e64 v67, -v61
	v_exp_f32_e64 v68, -v62
	v_exp_f32_e64 v69, -v63
	v_add_f32_e32 v66, 1.0, v66
	v_add_f32_e32 v67, 1.0, v67
	v_add_f32_e32 v68, 1.0, v68
	v_add_f32_e32 v69, 1.0, v69
	v_rcp_f32_e32 v66, v66
	v_rcp_f32_e32 v67, v67
	v_rcp_f32_e32 v68, v68
	v_rcp_f32_e32 v69, v69
	v_pk_mul_f32 v[58:59], v[62:63], v[58:59]
	v_pk_mul_f32 v[56:57], v[60:61], v[56:57]
	v_pk_mul_f32 v[56:57], v[56:57], v[66:67]
	v_pk_mul_f32 v[58:59], v[58:59], v[68:69]
	v_cvt_pk_bf16_f32 v56, v56, v57
	v_cvt_pk_bf16_f32 v57, v58, v59
	v_add_u32_e32 v64, 0x80, v170
	v_mad_i64_i32 v[64:65], s[16:17], v64, s57, v[142:143]
	v_lshl_add_u64 v[64:65], v[64:65], 0, v[140:141]
	global_store_dwordx2 v[64:65], v[56:57], off
	v_exp_f32_e64 v50, -v44
	v_exp_f32_e64 v51, -v45
	v_exp_f32_e64 v52, -v46
	v_exp_f32_e64 v53, -v47
	v_add_f32_e32 v50, 1.0, v50
	v_add_f32_e32 v51, 1.0, v51
	v_add_f32_e32 v52, 1.0, v52
	v_add_f32_e32 v53, 1.0, v53
	v_rcp_f32_e32 v50, v50
	v_rcp_f32_e32 v51, v51
	v_rcp_f32_e32 v52, v52
	v_rcp_f32_e32 v53, v53
	v_pk_mul_f32 v[42:43], v[46:47], v[42:43]
	v_pk_mul_f32 v[40:41], v[44:45], v[40:41]
	v_pk_mul_f32 v[40:41], v[40:41], v[50:51]
	v_pk_mul_f32 v[42:43], v[42:43], v[52:53]
	v_cvt_pk_bf16_f32 v40, v40, v41
	v_cvt_pk_bf16_f32 v41, v42, v43
	v_add_u32_e32 v48, 0x90, v170
	v_mad_i64_i32 v[48:49], s[16:17], v48, s57, v[142:143]
	v_lshl_add_u64 v[48:49], v[48:49], 0, v[140:141]
	global_store_dwordx2 v[48:49], v[40:41], off
	v_exp_f32_e64 v34, -v28
	v_exp_f32_e64 v35, -v29
	v_exp_f32_e64 v36, -v30
	v_exp_f32_e64 v37, -v31
	v_add_f32_e32 v34, 1.0, v34
	v_add_f32_e32 v35, 1.0, v35
	v_add_f32_e32 v36, 1.0, v36
	v_add_f32_e32 v37, 1.0, v37
	v_rcp_f32_e32 v34, v34
	v_rcp_f32_e32 v35, v35
	v_rcp_f32_e32 v36, v36
	v_rcp_f32_e32 v37, v37
	v_pk_mul_f32 v[26:27], v[30:31], v[26:27]
	v_pk_mul_f32 v[24:25], v[28:29], v[24:25]
	v_pk_mul_f32 v[24:25], v[24:25], v[34:35]
	v_pk_mul_f32 v[26:27], v[26:27], v[36:37]
	v_cvt_pk_bf16_f32 v24, v24, v25
	v_cvt_pk_bf16_f32 v25, v26, v27
	v_add_u32_e32 v32, 0xa0, v170
	v_mad_i64_i32 v[32:33], s[16:17], v32, s57, v[142:143]
	v_lshl_add_u64 v[32:33], v[32:33], 0, v[140:141]
	global_store_dwordx2 v[32:33], v[24:25], off
	v_exp_f32_e64 v18, -v12
	v_exp_f32_e64 v19, -v13
	v_exp_f32_e64 v20, -v14
	v_exp_f32_e64 v21, -v15
	v_add_f32_e32 v18, 1.0, v18
	v_add_f32_e32 v19, 1.0, v19
	v_add_f32_e32 v20, 1.0, v20
	v_add_f32_e32 v21, 1.0, v21
	v_rcp_f32_e32 v18, v18
	v_rcp_f32_e32 v19, v19
	v_rcp_f32_e32 v20, v20
	v_rcp_f32_e32 v21, v21
	v_pk_mul_f32 v[10:11], v[14:15], v[10:11]
	v_pk_mul_f32 v[8:9], v[12:13], v[8:9]
	v_pk_mul_f32 v[8:9], v[8:9], v[18:19]
	v_pk_mul_f32 v[10:11], v[10:11], v[20:21]
	v_cvt_pk_bf16_f32 v8, v8, v9
	v_cvt_pk_bf16_f32 v9, v10, v11
	v_add_u32_e32 v16, 0xb0, v170
	v_mad_i64_i32 v[16:17], s[16:17], v16, s57, v[142:143]
	v_lshl_add_u64 v[16:17], v[16:17], 0, v[140:141]
	global_store_dwordx2 v[16:17], v[8:9], off
	s_and_b64 vcc, exec, s[2:3]
	s_mov_b32 s61, s58
	s_mov_b32 s60, s59
	s_mov_b64 s[18:19], s[0:1]
	s_mov_b64 s[16:17], s[4:5]
